# conv items: the 46 input rows are requested one item ahead (during the previous item's LayerNorm stage / in the phase preamble), item start waits only for the weight loads
# speedup vs baseline: 1.0150x; 1.0090x over previous
.LBB0_552:
	s_bitcmp0_b32 s66, 1
	s_cselect_b64 s[0:1], -1, 0
	s_and_b64 s[0:1], s[0:1], s[24:25]
	s_and_b64 s[0:1], s[0:1], s[52:53]
	s_andn2_b64 vcc, exec, s[0:1]
	s_cbranch_vccnz .LBB0_557
	s_movk_i32 s0, 0x600
	v_cmp_gt_i32_e32 vcc, s0, v1
	s_and_saveexec_b64 s[0:1], vcc
	s_cbranch_execz .LBB0_556
	v_lshlrev_b32_e32 v2, 1, v212
	v_readlane_b32 s4, v245, 16
	v_and_b32_e32 v4, 0x1fe, v2
	v_readlane_b32 s5, v245, 17
	v_readlane_b32 s6, v245, 18
	v_readlane_b32 s7, v245, 19
	v_readlane_b32 s8, v245, 20
	v_readlane_b32 s9, v245, 21
	v_readlane_b32 s10, v245, 22
	v_readlane_b32 s11, v245, 23
	v_lshlrev_b32_e32 v2, 2, v4
	v_mov_b32_e32 v3, 0
	v_readlane_b32 s12, v245, 24
	v_readlane_b32 s13, v245, 25
	v_readlane_b32 s14, v245, 26
	v_readlane_b32 s15, v245, 27
	s_mov_b64 s[4:5], s[8:9]
	v_lshl_add_u64 v[18:19], s[4:5], 0, v[2:3]
	s_mov_b64 s[4:5], 0x1000
	v_lshl_add_u64 v[20:21], v[18:19], 0, s[4:5]
	s_mov_b64 s[4:5], 0x1800
	v_lshl_add_u64 v[22:23], v[18:19], 0, s[4:5]
	s_mov_b64 s[4:5], 0x2000
	v_lshl_add_u64 v[24:25], v[18:19], 0, s[4:5]
	s_mov_b64 s[4:5], 0x2800
	v_lshl_add_u64 v[26:27], v[18:19], 0, s[4:5]
	s_mov_b64 s[4:5], 0x3000
	v_lshl_add_u64 v[28:29], v[18:19], 0, s[4:5]
	s_mov_b64 s[4:5], 0x3800
	v_lshl_add_u64 v[30:31], v[18:19], 0, s[4:5]
	s_mov_b64 s[4:5], 0x4000
	v_lshl_add_u64 v[32:33], v[18:19], 0, s[4:5]
	s_mov_b64 s[4:5], 0x4800
	v_lshl_add_u64 v[34:35], v[18:19], 0, s[4:5]
	s_mov_b64 s[4:5], 0x5000
	v_lshl_add_u64 v[36:37], v[18:19], 0, s[4:5]
	s_mov_b64 s[4:5], 0x5800
	v_lshl_add_u64 v[38:39], v[18:19], 0, s[4:5]
	s_mov_b64 s[4:5], 0x6000
	v_lshl_add_u64 v[40:41], v[18:19], 0, s[4:5]
	s_mov_b64 s[4:5], 0x6800
	v_lshl_add_u64 v[42:43], v[18:19], 0, s[4:5]
	s_mov_b64 s[4:5], 0x7000
	v_lshl_add_u64 v[44:45], v[18:19], 0, s[4:5]
	s_mov_b64 s[4:5], 0x7800
	v_lshl_add_u64 v[46:47], v[18:19], 0, s[4:5]
	s_mov_b64 s[4:5], 0x8000
	v_lshl_add_u64 v[48:49], v[18:19], 0, s[4:5]
	s_mov_b64 s[4:5], 0x8800
	v_lshl_add_u64 v[50:51], v[18:19], 0, s[4:5]
	s_mov_b64 s[4:5], 0x9000
	v_lshl_add_u64 v[52:53], v[18:19], 0, s[4:5]
	s_mov_b64 s[4:5], 0x9800
	v_lshl_add_u64 v[54:55], v[18:19], 0, s[4:5]
	s_mov_b64 s[4:5], 0xa000
	v_lshl_add_u64 v[56:57], v[18:19], 0, s[4:5]
	s_mov_b64 s[4:5], 0xa800
	v_lshl_add_u64 v[58:59], v[18:19], 0, s[4:5]
	s_mov_b64 s[4:5], 0xb000
	v_lshl_add_u64 v[60:61], v[18:19], 0, s[4:5]
	s_mov_b64 s[4:5], 0xb800
	v_lshl_add_u64 v[62:63], v[18:19], 0, s[4:5]
	s_mov_b64 s[4:5], 0xc000
	v_lshl_add_u64 v[64:65], v[18:19], 0, s[4:5]
	s_mov_b64 s[4:5], 0xc800
	v_lshl_add_u64 v[66:67], v[18:19], 0, s[4:5]
	s_mov_b64 s[4:5], 0xd000
	v_lshl_add_u64 v[68:69], v[18:19], 0, s[4:5]
	s_mov_b64 s[4:5], 0xd800
	v_lshl_add_u64 v[70:71], v[18:19], 0, s[4:5]
	s_mov_b64 s[4:5], 0xe000
	v_lshl_add_u64 v[72:73], v[18:19], 0, s[4:5]
	s_mov_b64 s[4:5], 0xe800
	v_lshl_add_u64 v[74:75], v[18:19], 0, s[4:5]
	s_mov_b64 s[4:5], 0xf000
	v_lshlrev_b32_e32 v4, 1, v4
	v_mov_b32_e32 v5, v3
	s_mov_b64 s[6:7], s[10:11]
	v_lshl_add_u64 v[76:77], v[18:19], 0, s[4:5]
	v_lshl_add_u64 v[4:5], s[96:97], 0, v[4:5]
	s_mov_b64 s[4:5], 0xd3a4000
	v_lshl_add_u64 v[78:79], v[4:5], 0, s[4:5]
	v_lshl_add_u64 v[80:81], s[6:7], 0, v[2:3]
	v_add_u32_e32 v214, v160, v2
	v_lshlrev_b32_e32 v2, 2, v212
	v_lshrrev_b32_e32 v5, 4, v212
	v_and_b32_e32 v4, 0xfc, v2
	v_and_b32_e32 v215, 12, v5
	v_mbcnt_hi_u32_b32 v5, -1, v213
	s_mov_b64 s[8:9], s[12:13]
	s_mov_b64 s[10:11], s[14:15]
	v_lshlrev_b32_e32 v2, 2, v4
	v_and_b32_e32 v6, 64, v5
	v_lshlrev_b32_e32 v7, 11, v215
	v_lshl_add_u64 v[82:83], s[8:9], 0, v[2:3]
	v_lshl_add_u64 v[84:85], s[10:11], 0, v[2:3]
	v_add_u32_e32 v6, 64, v6
	v_add3_u32 v216, v160, v7, v2
	v_xor_b32_e32 v2, 32, v5
	v_cmp_lt_i32_e32 vcc, v2, v6
	s_mov_b64 s[4:5], 0x5ba0000
	v_readlane_b32 s16, v245, 28
	v_cndmask_b32_e32 v2, v5, v2, vcc
	v_lshlrev_b32_e32 v217, 2, v2
	v_xor_b32_e32 v2, 16, v5
	v_cmp_lt_i32_e32 vcc, v2, v6
	v_readlane_b32 s17, v245, 29
	v_readlane_b32 s18, v245, 30
	v_cndmask_b32_e32 v2, v5, v2, vcc
	v_lshlrev_b32_e32 v218, 2, v2
	v_xor_b32_e32 v2, 8, v5
	v_cmp_lt_i32_e32 vcc, v2, v6
	v_readlane_b32 s19, v245, 31
	v_add_u32_e32 v223, 0x800, v216
	v_cndmask_b32_e32 v2, v5, v2, vcc
	v_lshlrev_b32_e32 v219, 2, v2
	v_xor_b32_e32 v2, 4, v5
	v_cmp_lt_i32_e32 vcc, v2, v6
	s_movk_i32 s7, 0x1000
	v_add_u32_e32 v224, 0x1000, v216
	v_cndmask_b32_e32 v2, v5, v2, vcc
	v_lshlrev_b32_e32 v220, 2, v2
	v_xor_b32_e32 v2, 2, v5
	v_cmp_lt_i32_e32 vcc, v2, v6
	v_add_u32_e32 v225, 0x1800, v216
	s_lshl_b32 s8, s62, 1
	v_cndmask_b32_e32 v2, v5, v2, vcc
	v_lshlrev_b32_e32 v221, 2, v2
	v_xor_b32_e32 v2, 1, v5
	v_cmp_lt_i32_e32 vcc, v2, v6
	s_lshl_b32 s9, s62, 5
	s_movk_i32 s10, 0x200
	v_cndmask_b32_e32 v2, v5, v2, vcc
	v_lshlrev_b32_e32 v222, 2, v2
	v_lshlrev_b32_e32 v2, 1, v4
	v_lshl_add_u64 v[2:3], s[96:97], 0, v[2:3]
	v_lshl_add_u64 v[86:87], v[2:3], 0, s[4:5]
	s_mov_b64 s[4:5], 0x13a0000
	v_lshl_add_u64 v[88:89], v[2:3], 0, s[4:5]
	v_lshlrev_b32_e32 v2, 4, v131
	v_lshl_add_u32 v2, s2, 5, v2
	v_add_u32_e32 v226, 0xffffe000, v2
	s_mov_b64 s[4:5], 0
	s_movk_i32 s11, 0x2001
	s_movk_i32 s12, 0x2000
	s_movk_i32 s13, 0x3000
	s_movk_i32 s14, 0x4000
	s_movk_i32 s15, 0x5000
	s_movk_i32 s16, 0x6000
	s_movk_i32 s17, 0x7000
	s_mov_b32 s18, 0x8000
	s_mov_b32 s19, 0x9000
	s_mov_b32 s20, 0xa000
	s_mov_b32 s21, 0xb000
	s_mov_b32 s6, 0x3b000000
	s_mov_b32 s22, 0x800000
	s_movk_i32 s23, 0x5ff
	v_lshrrev_b32_e32 v253, 12, v226
	v_cmp_gt_i32_e64 s[98:99], s10, v1
	v_lshrrev_b32_e32 v252, 4, v1
	v_add_u32_e32 v253, 32, v253
	v_cndmask_b32_e64 v252, v253, v252, s[98:99]
	v_lshlrev_b32_e32 v252, 5, v252
	v_add3_u32 v252, v226, v252, s11
	v_ashrrev_i32_e32 v253, 31, v252
	v_lshlrev_b64 v[252:253], 10, v[252:253]
	v_lshl_add_u64 v[252:253], v[78:79], 0, v[252:253]
	s_mov_b64 s[100:101], 0x1000
	v_lshl_add_u64 v[252:253], v[252:253], 0, s[100:101]
	s_mov_b64 s[100:101], 0x2000
	global_load_dword v146, v[252:253], off offset:-4096
	global_load_dword v145, v[252:253], off offset:-3072
	global_load_dword v150, v[252:253], off offset:-2048
	global_load_dword v152, v[252:253], off offset:-1024
	global_load_dword v156, v[252:253], off
	global_load_dword v158, v[252:253], off offset:1024
	global_load_dword v160, v[252:253], off offset:2048
	global_load_dword v164, v[252:253], off offset:3072
	v_lshl_add_u64 v[252:253], v[252:253], 0, s[100:101]
	global_load_dword v166, v[252:253], off offset:-4096
	global_load_dword v168, v[252:253], off offset:-3072
	global_load_dword v172, v[252:253], off offset:-2048
	global_load_dword v174, v[252:253], off offset:-1024
	global_load_dword v176, v[252:253], off
	global_load_dword v144, v[252:253], off offset:1024
	global_load_dword v251, v[252:253], off offset:2048
	global_load_dword v250, v[252:253], off offset:3072
	v_lshl_add_u64 v[252:253], v[252:253], 0, s[100:101]
	global_load_dword v249, v[252:253], off offset:-4096
	global_load_dword v248, v[252:253], off offset:-3072
	global_load_dword v246, v[252:253], off offset:-2048
	global_load_dword v247, v[252:253], off offset:-1024
	global_load_dword v147, v[252:253], off
	global_load_dword v151, v[252:253], off offset:1024
	global_load_dword v153, v[252:253], off offset:2048
	global_load_dword v157, v[252:253], off offset:3072
	v_lshl_add_u64 v[252:253], v[252:253], 0, s[100:101]
	global_load_dword v159, v[252:253], off offset:-4096
	global_load_dword v161, v[252:253], off offset:-3072
	global_load_dword v165, v[252:253], off offset:-2048
	global_load_dword v167, v[252:253], off offset:-1024
	global_load_dword v169, v[252:253], off
	global_load_dword v173, v[252:253], off offset:1024
	global_load_dword v175, v[252:253], off offset:2048
	global_load_dword v177, v[252:253], off offset:3072
	v_lshl_add_u64 v[252:253], v[252:253], 0, s[100:101]
	global_load_dword v181, v[252:253], off offset:-4096
	global_load_dword v183, v[252:253], off offset:-3072
	global_load_dword v185, v[252:253], off offset:-2048
	global_load_dword v189, v[252:253], off offset:-1024
	global_load_dword v191, v[252:253], off
	global_load_dword v193, v[252:253], off offset:1024
	global_load_dword v195, v[252:253], off offset:2048
	global_load_dword v201, v[252:253], off offset:3072
	v_lshl_add_u64 v[252:253], v[252:253], 0, s[100:101]
	global_load_dword v203, v[252:253], off offset:-4096
	global_load_dword v205, v[252:253], off offset:-3072
	global_load_dword v207, v[252:253], off offset:-2048
	global_load_dword v209, v[252:253], off offset:-1024
	global_load_dword v211, v[252:253], off
	global_load_dword v227, v[252:253], off offset:1024
.LBB0_555:
	v_lshrrev_b32_e32 v3, 12, v226
	v_cmp_gt_i32_e32 vcc, s10, v1
	v_lshrrev_b32_e32 v2, 4, v1
	v_add_u32_e32 v3, 32, v3
	v_cndmask_b32_e32 v2, v3, v2, vcc
	v_lshlrev_b32_e32 v2, 5, v2
	v_add3_u32 v2, v226, v2, s11
	v_ashrrev_i32_e32 v3, 31, v2
	v_lshlrev_b64 v[136:137], 10, v[2:3]
	v_lshl_add_u64 v[148:149], v[78:79], 0, v[136:137]
	s_waitcnt lgkmcnt(0)
	s_nop 0
	s_barrier
	s_nop 0
	global_load_dwordx2 v[134:135], v[18:19], off
	global_load_dwordx2 v[132:133], v[18:19], off offset:2048
	global_load_dwordx2 v[130:131], v[20:21], off
	global_load_dwordx2 v[128:129], v[22:23], off
	global_load_dwordx2 v[2:3], v[24:25], off
	global_load_dwordx2 v[4:5], v[26:27], off
	global_load_dwordx2 v[6:7], v[28:29], off
	global_load_dwordx2 v[8:9], v[30:31], off
	global_load_dwordx2 v[10:11], v[32:33], off
	global_load_dwordx2 v[12:13], v[34:35], off
	global_load_dwordx2 v[14:15], v[36:37], off
	global_load_dwordx2 v[16:17], v[38:39], off
	global_load_dwordx2 v[90:91], v[40:41], off
	global_load_dwordx2 v[92:93], v[42:43], off
	global_load_dwordx2 v[94:95], v[44:45], off
	global_load_dwordx2 v[96:97], v[46:47], off
	global_load_dwordx2 v[98:99], v[48:49], off
	global_load_dwordx2 v[100:101], v[50:51], off
	global_load_dwordx2 v[102:103], v[52:53], off
	global_load_dwordx2 v[104:105], v[54:55], off
	global_load_dwordx2 v[106:107], v[56:57], off
	global_load_dwordx2 v[108:109], v[58:59], off
	global_load_dwordx2 v[110:111], v[60:61], off
	global_load_dwordx2 v[112:113], v[62:63], off
	global_load_dwordx2 v[114:115], v[64:65], off
	global_load_dwordx2 v[116:117], v[66:67], off
	global_load_dwordx2 v[118:119], v[68:69], off
	global_load_dwordx2 v[120:121], v[70:71], off
	global_load_dwordx2 v[122:123], v[72:73], off
	global_load_dwordx2 v[124:125], v[74:75], off
	global_load_dwordx2 v[126:127], v[76:77], off
	global_load_dwordx2 v[136:137], v[80:81], off
	s_waitcnt vmcnt(32)
	v_mov_b32_e32 v138, v246
	v_mov_b32_e32 v139, v247
	v_mov_b32_e32 v140, v248
	v_mov_b32_e32 v141, v249
	v_mov_b32_e32 v142, v250
	v_mov_b32_e32 v143, v251
	v_add_u32_e32 v1, s8, v1
	s_nop 0
	v_lshlrev_b32_e32 v178, 16, v156
	s_nop 0
	v_lshlrev_b32_e32 v170, 16, v152
	s_nop 0
	v_and_b32_e32 v171, 0xffff0000, v152
	s_nop 0
	v_and_b32_e32 v179, 0xffff0000, v156
	s_nop 0
	v_lshlrev_b32_e32 v186, 16, v158
	v_and_b32_e32 v187, 0xffff0000, v158
	s_nop 0
	v_lshlrev_b32_e32 v162, 16, v150
	s_nop 0
	v_lshlrev_b32_e32 v154, 16, v145
	v_and_b32_e32 v155, 0xffff0000, v145
	v_and_b32_e32 v163, 0xffff0000, v150
	v_lshlrev_b32_e32 v196, 16, v160
	v_and_b32_e32 v197, 0xffff0000, v160
	v_lshlrev_b32_e32 v198, 16, v164
	v_and_b32_e32 v199, 0xffff0000, v164
	v_lshlrev_b32_e32 v150, 16, v151
	v_and_b32_e32 v151, 0xffff0000, v151
	v_lshlrev_b32_e32 v152, 16, v153
	v_and_b32_e32 v153, 0xffff0000, v153
	v_lshlrev_b32_e32 v156, 16, v157
	v_and_b32_e32 v157, 0xffff0000, v157
	v_lshlrev_b32_e32 v158, 16, v159
	v_and_b32_e32 v159, 0xffff0000, v159
	v_lshlrev_b32_e32 v160, 16, v161
	v_and_b32_e32 v161, 0xffff0000, v161
	v_lshlrev_b32_e32 v164, 16, v165
	v_and_b32_e32 v165, 0xffff0000, v165
	v_lshlrev_b32_e32 v180, 16, v181
	v_and_b32_e32 v181, 0xffff0000, v181
	v_lshlrev_b32_e32 v182, 16, v183
	v_and_b32_e32 v183, 0xffff0000, v183
	v_lshlrev_b32_e32 v184, 16, v185
	v_and_b32_e32 v185, 0xffff0000, v185
	v_lshlrev_b32_e32 v188, 16, v189
	v_and_b32_e32 v189, 0xffff0000, v189
	v_lshlrev_b32_e32 v190, 16, v191
	v_and_b32_e32 v191, 0xffff0000, v191
	v_lshlrev_b32_e32 v192, 16, v193
	v_and_b32_e32 v193, 0xffff0000, v193
	v_lshlrev_b32_e32 v194, 16, v195
	v_and_b32_e32 v195, 0xffff0000, v195
	v_lshlrev_b32_e32 v200, 16, v201
	v_and_b32_e32 v201, 0xffff0000, v201
	v_lshlrev_b32_e32 v202, 16, v203
	v_and_b32_e32 v203, 0xffff0000, v203
	v_lshlrev_b32_e32 v204, 16, v205
	v_and_b32_e32 v205, 0xffff0000, v205
	s_waitcnt vmcnt(0)
	v_lshlrev_b32_e32 v148, 16, v146
	v_and_b32_e32 v149, 0xffff0000, v146
	v_pk_fma_f32 v[148:149], v[148:149], v[134:135], v[136:137]
	v_lshlrev_b32_e32 v146, 16, v147
	v_pk_fma_f32 v[148:149], v[154:155], v[132:133], v[148:149]
	v_pk_fma_f32 v[154:155], v[154:155], v[134:135], v[136:137]
	v_pk_fma_f32 v[148:149], v[162:163], v[130:131], v[148:149]
	v_pk_fma_f32 v[154:155], v[162:163], v[132:133], v[154:155]
	v_pk_fma_f32 v[162:163], v[162:163], v[134:135], v[136:137]
	v_pk_fma_f32 v[148:149], v[170:171], v[128:129], v[148:149]
	v_pk_fma_f32 v[154:155], v[170:171], v[130:131], v[154:155]
	v_pk_fma_f32 v[162:163], v[170:171], v[132:133], v[162:163]
	v_pk_fma_f32 v[170:171], v[170:171], v[134:135], v[136:137]
	v_pk_fma_f32 v[148:149], v[178:179], v[2:3], v[148:149]
	v_pk_fma_f32 v[154:155], v[178:179], v[128:129], v[154:155]
	v_pk_fma_f32 v[162:163], v[178:179], v[130:131], v[162:163]
	v_pk_fma_f32 v[170:171], v[178:179], v[132:133], v[170:171]
	v_pk_fma_f32 v[178:179], v[178:179], v[134:135], v[136:137]
	v_pk_fma_f32 v[148:149], v[186:187], v[4:5], v[148:149]
	v_pk_fma_f32 v[154:155], v[186:187], v[2:3], v[154:155]
	v_pk_fma_f32 v[162:163], v[186:187], v[128:129], v[162:163]
	v_pk_fma_f32 v[170:171], v[186:187], v[130:131], v[170:171]
	v_pk_fma_f32 v[178:179], v[186:187], v[132:133], v[178:179]
	v_pk_fma_f32 v[186:187], v[186:187], v[134:135], v[136:137]
	v_pk_fma_f32 v[148:149], v[196:197], v[6:7], v[148:149]
	v_pk_fma_f32 v[154:155], v[196:197], v[4:5], v[154:155]
	v_pk_fma_f32 v[162:163], v[196:197], v[2:3], v[162:163]
	v_pk_fma_f32 v[170:171], v[196:197], v[128:129], v[170:171]
	v_pk_fma_f32 v[178:179], v[196:197], v[130:131], v[178:179]
	v_pk_fma_f32 v[186:187], v[196:197], v[132:133], v[186:187]
	v_pk_fma_f32 v[196:197], v[196:197], v[134:135], v[136:137]
	v_pk_fma_f32 v[148:149], v[198:199], v[8:9], v[148:149]
	v_pk_fma_f32 v[154:155], v[198:199], v[6:7], v[154:155]
	v_pk_fma_f32 v[162:163], v[198:199], v[4:5], v[162:163]
	v_pk_fma_f32 v[170:171], v[198:199], v[2:3], v[170:171]
	v_pk_fma_f32 v[178:179], v[198:199], v[128:129], v[178:179]
	v_pk_fma_f32 v[186:187], v[198:199], v[130:131], v[186:187]
	v_pk_fma_f32 v[228:229], v[198:199], v[132:133], v[196:197]
	v_pk_fma_f32 v[198:199], v[198:199], v[134:135], v[136:137]
	v_lshlrev_b32_e32 v196, 16, v166
	v_and_b32_e32 v197, 0xffff0000, v166
	v_pk_fma_f32 v[148:149], v[196:197], v[10:11], v[148:149]
	v_pk_fma_f32 v[154:155], v[196:197], v[8:9], v[154:155]
	v_pk_fma_f32 v[162:163], v[196:197], v[6:7], v[162:163]
	v_pk_fma_f32 v[170:171], v[196:197], v[4:5], v[170:171]
	v_pk_fma_f32 v[178:179], v[196:197], v[2:3], v[178:179]
	v_pk_fma_f32 v[186:187], v[196:197], v[128:129], v[186:187]
	v_pk_fma_f32 v[230:231], v[196:197], v[132:133], v[198:199]
	v_lshlrev_b32_e32 v198, 16, v168
	v_and_b32_e32 v199, 0xffff0000, v168
	v_pk_fma_f32 v[228:229], v[196:197], v[130:131], v[228:229]
	v_pk_fma_f32 v[148:149], v[198:199], v[12:13], v[148:149]
	v_pk_fma_f32 v[154:155], v[198:199], v[10:11], v[154:155]
	v_pk_fma_f32 v[162:163], v[198:199], v[8:9], v[162:163]
	v_pk_fma_f32 v[170:171], v[198:199], v[6:7], v[170:171]
	v_pk_fma_f32 v[178:179], v[198:199], v[4:5], v[178:179]
	v_pk_fma_f32 v[232:233], v[198:199], v[2:3], v[186:187]
	v_lshlrev_b32_e32 v186, 16, v172
	v_and_b32_e32 v187, 0xffff0000, v172
	v_pk_fma_f32 v[196:197], v[196:197], v[134:135], v[136:137]
	v_pk_fma_f32 v[228:229], v[198:199], v[128:129], v[228:229]
	v_pk_fma_f32 v[230:231], v[198:199], v[130:131], v[230:231]
	v_pk_fma_f32 v[148:149], v[186:187], v[14:15], v[148:149]
	v_pk_fma_f32 v[154:155], v[186:187], v[12:13], v[154:155]
	v_pk_fma_f32 v[162:163], v[186:187], v[10:11], v[162:163]
	v_pk_fma_f32 v[170:171], v[186:187], v[8:9], v[170:171]
	v_pk_fma_f32 v[234:235], v[186:187], v[6:7], v[178:179]
	v_lshlrev_b32_e32 v178, 16, v174
	v_and_b32_e32 v179, 0xffff0000, v174
	v_pk_fma_f32 v[196:197], v[198:199], v[132:133], v[196:197]
	v_pk_fma_f32 v[198:199], v[198:199], v[134:135], v[136:137]
	v_pk_fma_f32 v[232:233], v[186:187], v[4:5], v[232:233]
	v_pk_fma_f32 v[228:229], v[186:187], v[2:3], v[228:229]
	v_pk_fma_f32 v[230:231], v[186:187], v[128:129], v[230:231]
	v_pk_fma_f32 v[148:149], v[178:179], v[16:17], v[148:149]
	v_pk_fma_f32 v[154:155], v[178:179], v[14:15], v[154:155]
	v_pk_fma_f32 v[162:163], v[178:179], v[12:13], v[162:163]
	v_pk_fma_f32 v[236:237], v[178:179], v[10:11], v[170:171]
	v_lshlrev_b32_e32 v170, 16, v176
	v_and_b32_e32 v171, 0xffff0000, v176
	v_pk_fma_f32 v[196:197], v[186:187], v[130:131], v[196:197]
	v_pk_fma_f32 v[198:199], v[186:187], v[132:133], v[198:199]
	v_pk_fma_f32 v[186:187], v[186:187], v[134:135], v[136:137]
	v_pk_fma_f32 v[234:235], v[178:179], v[8:9], v[234:235]
	v_pk_fma_f32 v[232:233], v[178:179], v[6:7], v[232:233]
	v_pk_fma_f32 v[228:229], v[178:179], v[4:5], v[228:229]
	v_pk_fma_f32 v[230:231], v[178:179], v[2:3], v[230:231]
	v_pk_fma_f32 v[148:149], v[170:171], v[90:91], v[148:149]
	v_pk_fma_f32 v[154:155], v[170:171], v[16:17], v[154:155]
	v_pk_fma_f32 v[238:239], v[170:171], v[14:15], v[162:163]
	v_lshlrev_b32_e32 v162, 16, v144
	v_and_b32_e32 v163, 0xffff0000, v144
	v_pk_fma_f32 v[196:197], v[178:179], v[128:129], v[196:197]
	v_pk_fma_f32 v[198:199], v[178:179], v[130:131], v[198:199]
	v_pk_fma_f32 v[186:187], v[178:179], v[132:133], v[186:187]
	v_pk_fma_f32 v[178:179], v[178:179], v[134:135], v[136:137]
	v_pk_fma_f32 v[236:237], v[170:171], v[12:13], v[236:237]
	v_pk_fma_f32 v[234:235], v[170:171], v[10:11], v[234:235]
	v_pk_fma_f32 v[232:233], v[170:171], v[8:9], v[232:233]
	v_pk_fma_f32 v[228:229], v[170:171], v[6:7], v[228:229]
	v_pk_fma_f32 v[230:231], v[170:171], v[4:5], v[230:231]
	v_pk_fma_f32 v[144:145], v[162:163], v[92:93], v[148:149]
	v_pk_fma_f32 v[148:149], v[162:163], v[90:91], v[154:155]
	v_lshlrev_b32_e32 v154, 16, v143
	v_and_b32_e32 v155, 0xffff0000, v143
	v_pk_fma_f32 v[196:197], v[170:171], v[2:3], v[196:197]
	v_pk_fma_f32 v[198:199], v[170:171], v[128:129], v[198:199]
	v_pk_fma_f32 v[186:187], v[170:171], v[130:131], v[186:187]
	v_pk_fma_f32 v[178:179], v[170:171], v[132:133], v[178:179]
	v_pk_fma_f32 v[170:171], v[170:171], v[134:135], v[136:137]
	v_pk_fma_f32 v[238:239], v[162:163], v[16:17], v[238:239]
	v_pk_fma_f32 v[236:237], v[162:163], v[14:15], v[236:237]
	v_pk_fma_f32 v[234:235], v[162:163], v[12:13], v[234:235]
	v_pk_fma_f32 v[232:233], v[162:163], v[10:11], v[232:233]
	v_pk_fma_f32 v[228:229], v[162:163], v[8:9], v[228:229]
	v_pk_fma_f32 v[230:231], v[162:163], v[6:7], v[230:231]
	v_pk_fma_f32 v[144:145], v[154:155], v[94:95], v[144:145]
	v_pk_fma_f32 v[240:241], v[154:155], v[92:93], v[148:149]
	v_lshlrev_b32_e32 v148, 16, v142
	v_and_b32_e32 v149, 0xffff0000, v142
	v_pk_fma_f32 v[196:197], v[162:163], v[4:5], v[196:197]
	v_pk_fma_f32 v[198:199], v[162:163], v[2:3], v[198:199]
	v_pk_fma_f32 v[186:187], v[162:163], v[128:129], v[186:187]
	v_pk_fma_f32 v[178:179], v[162:163], v[130:131], v[178:179]
	v_pk_fma_f32 v[170:171], v[162:163], v[132:133], v[170:171]
	v_pk_fma_f32 v[162:163], v[162:163], v[134:135], v[136:137]
	v_pk_fma_f32 v[238:239], v[154:155], v[90:91], v[238:239]
	v_pk_fma_f32 v[236:237], v[154:155], v[16:17], v[236:237]
	v_pk_fma_f32 v[234:235], v[154:155], v[14:15], v[234:235]
	v_pk_fma_f32 v[232:233], v[154:155], v[12:13], v[232:233]
	v_pk_fma_f32 v[228:229], v[154:155], v[10:11], v[228:229]
	v_pk_fma_f32 v[230:231], v[154:155], v[8:9], v[230:231]
	v_pk_fma_f32 v[142:143], v[148:149], v[96:97], v[144:145]
	v_lshlrev_b32_e32 v144, 16, v141
	v_and_b32_e32 v145, 0xffff0000, v141
	v_pk_fma_f32 v[196:197], v[154:155], v[6:7], v[196:197]
	v_pk_fma_f32 v[198:199], v[154:155], v[4:5], v[198:199]
	v_pk_fma_f32 v[186:187], v[154:155], v[2:3], v[186:187]
	v_pk_fma_f32 v[178:179], v[154:155], v[128:129], v[178:179]
	v_pk_fma_f32 v[170:171], v[154:155], v[130:131], v[170:171]
	v_pk_fma_f32 v[162:163], v[154:155], v[132:133], v[162:163]
	v_pk_fma_f32 v[154:155], v[154:155], v[134:135], v[136:137]
	v_pk_fma_f32 v[134:135], v[148:149], v[134:135], v[136:137]
	v_pk_fma_f32 v[242:243], v[144:145], v[98:99], v[142:143]
	v_lshlrev_b32_e32 v142, 16, v140
	v_and_b32_e32 v143, 0xffff0000, v140
	v_pk_fma_f32 v[154:155], v[148:149], v[132:133], v[154:155]
	v_pk_fma_f32 v[132:133], v[144:145], v[132:133], v[134:135]
	v_lshlrev_b32_e32 v140, 16, v138
	v_and_b32_e32 v141, 0xffff0000, v138
	v_pk_fma_f32 v[162:163], v[148:149], v[130:131], v[162:163]
	v_pk_fma_f32 v[154:155], v[144:145], v[130:131], v[154:155]
	v_pk_fma_f32 v[130:131], v[142:143], v[130:131], v[132:133]
	v_lshlrev_b32_e32 v138, 16, v139
	v_and_b32_e32 v139, 0xffff0000, v139
	v_pk_fma_f32 v[170:171], v[148:149], v[128:129], v[170:171]
	v_pk_fma_f32 v[162:163], v[144:145], v[128:129], v[162:163]
	v_pk_fma_f32 v[154:155], v[142:143], v[128:129], v[154:155]
	v_pk_fma_f32 v[128:129], v[140:141], v[128:129], v[130:131]
	v_and_b32_e32 v147, 0xffff0000, v147
	v_pk_fma_f32 v[178:179], v[148:149], v[2:3], v[178:179]
	v_pk_fma_f32 v[170:171], v[144:145], v[2:3], v[170:171]
	v_pk_fma_f32 v[162:163], v[142:143], v[2:3], v[162:163]
	v_pk_fma_f32 v[154:155], v[140:141], v[2:3], v[154:155]
	v_pk_fma_f32 v[2:3], v[138:139], v[2:3], v[128:129]
	v_pk_fma_f32 v[198:199], v[148:149], v[6:7], v[198:199]
	v_pk_fma_f32 v[2:3], v[146:147], v[4:5], v[2:3]
	v_pk_fma_f32 v[186:187], v[148:149], v[4:5], v[186:187]
	v_pk_fma_f32 v[178:179], v[144:145], v[4:5], v[178:179]
	v_pk_fma_f32 v[170:171], v[142:143], v[4:5], v[170:171]
	v_pk_fma_f32 v[162:163], v[140:141], v[4:5], v[162:163]
	v_pk_fma_f32 v[154:155], v[138:139], v[4:5], v[154:155]
	v_pk_fma_f32 v[2:3], v[150:151], v[6:7], v[2:3]
	v_pk_fma_f32 v[228:229], v[148:149], v[12:13], v[228:229]
	v_pk_fma_f32 v[230:231], v[148:149], v[10:11], v[230:231]
	v_pk_fma_f32 v[196:197], v[148:149], v[8:9], v[196:197]
	v_pk_fma_f32 v[198:199], v[144:145], v[8:9], v[198:199]
	v_pk_fma_f32 v[186:187], v[144:145], v[6:7], v[186:187]
	v_pk_fma_f32 v[178:179], v[142:143], v[6:7], v[178:179]
	v_pk_fma_f32 v[170:171], v[140:141], v[6:7], v[170:171]
	v_pk_fma_f32 v[162:163], v[138:139], v[6:7], v[162:163]
	v_pk_fma_f32 v[154:155], v[146:147], v[6:7], v[154:155]
	v_pk_fma_f32 v[2:3], v[152:153], v[8:9], v[2:3]
	v_pk_fma_f32 v[228:229], v[144:145], v[14:15], v[228:229]
	v_pk_fma_f32 v[230:231], v[144:145], v[12:13], v[230:231]
	v_pk_fma_f32 v[196:197], v[144:145], v[10:11], v[196:197]
	v_pk_fma_f32 v[198:199], v[142:143], v[10:11], v[198:199]
	v_pk_fma_f32 v[186:187], v[142:143], v[8:9], v[186:187]
	v_pk_fma_f32 v[178:179], v[140:141], v[8:9], v[178:179]
	v_pk_fma_f32 v[170:171], v[138:139], v[8:9], v[170:171]
	v_pk_fma_f32 v[162:163], v[146:147], v[8:9], v[162:163]
	v_pk_fma_f32 v[154:155], v[150:151], v[8:9], v[154:155]
	v_pk_fma_f32 v[2:3], v[156:157], v[10:11], v[2:3]
	v_pk_fma_f32 v[232:233], v[148:149], v[14:15], v[232:233]
	v_pk_fma_f32 v[228:229], v[142:143], v[16:17], v[228:229]
	v_pk_fma_f32 v[230:231], v[142:143], v[14:15], v[230:231]
	v_pk_fma_f32 v[196:197], v[142:143], v[12:13], v[196:197]
	v_pk_fma_f32 v[198:199], v[140:141], v[12:13], v[198:199]
	v_pk_fma_f32 v[186:187], v[140:141], v[10:11], v[186:187]
	v_pk_fma_f32 v[178:179], v[138:139], v[10:11], v[178:179]
	v_pk_fma_f32 v[170:171], v[146:147], v[10:11], v[170:171]
	v_pk_fma_f32 v[162:163], v[150:151], v[10:11], v[162:163]
	v_pk_fma_f32 v[154:155], v[152:153], v[10:11], v[154:155]
	v_pk_fma_f32 v[2:3], v[158:159], v[12:13], v[2:3]
	v_pk_fma_f32 v[234:235], v[148:149], v[16:17], v[234:235]
	v_pk_fma_f32 v[232:233], v[144:145], v[16:17], v[232:233]
	v_pk_fma_f32 v[228:229], v[140:141], v[90:91], v[228:229]
	v_pk_fma_f32 v[230:231], v[140:141], v[16:17], v[230:231]
	v_pk_fma_f32 v[196:197], v[140:141], v[14:15], v[196:197]
	v_pk_fma_f32 v[198:199], v[138:139], v[14:15], v[198:199]
	v_pk_fma_f32 v[186:187], v[138:139], v[12:13], v[186:187]
	v_pk_fma_f32 v[178:179], v[146:147], v[12:13], v[178:179]
	v_pk_fma_f32 v[170:171], v[150:151], v[12:13], v[170:171]
	v_pk_fma_f32 v[162:163], v[152:153], v[12:13], v[162:163]
	v_pk_fma_f32 v[154:155], v[156:157], v[12:13], v[154:155]
	v_pk_fma_f32 v[2:3], v[160:161], v[14:15], v[2:3]
	v_pk_fma_f32 v[236:237], v[148:149], v[90:91], v[236:237]
	v_pk_fma_f32 v[234:235], v[144:145], v[90:91], v[234:235]
	v_pk_fma_f32 v[232:233], v[142:143], v[90:91], v[232:233]
	v_pk_fma_f32 v[228:229], v[138:139], v[92:93], v[228:229]
	v_pk_fma_f32 v[230:231], v[138:139], v[90:91], v[230:231]
	v_lshlrev_b32_e32 v166, 16, v167
	v_and_b32_e32 v167, 0xffff0000, v167
	v_pk_fma_f32 v[196:197], v[138:139], v[16:17], v[196:197]
	v_pk_fma_f32 v[198:199], v[146:147], v[16:17], v[198:199]
	v_pk_fma_f32 v[186:187], v[146:147], v[14:15], v[186:187]
	v_pk_fma_f32 v[178:179], v[150:151], v[14:15], v[178:179]
	v_pk_fma_f32 v[170:171], v[152:153], v[14:15], v[170:171]
	v_pk_fma_f32 v[162:163], v[156:157], v[14:15], v[162:163]
	v_pk_fma_f32 v[154:155], v[158:159], v[14:15], v[154:155]
	v_pk_fma_f32 v[2:3], v[164:165], v[16:17], v[2:3]
	v_pk_fma_f32 v[240:241], v[148:149], v[94:95], v[240:241]
	v_pk_fma_f32 v[238:239], v[148:149], v[92:93], v[238:239]
	v_pk_fma_f32 v[236:237], v[144:145], v[92:93], v[236:237]
	v_pk_fma_f32 v[234:235], v[142:143], v[92:93], v[234:235]
	v_pk_fma_f32 v[232:233], v[140:141], v[92:93], v[232:233]
	v_pk_fma_f32 v[228:229], v[146:147], v[94:95], v[228:229]
	v_pk_fma_f32 v[230:231], v[146:147], v[92:93], v[230:231]
	v_lshlrev_b32_e32 v168, 16, v169
	v_and_b32_e32 v169, 0xffff0000, v169
	v_pk_fma_f32 v[196:197], v[146:147], v[90:91], v[196:197]
	v_pk_fma_f32 v[198:199], v[150:151], v[90:91], v[198:199]
	v_pk_fma_f32 v[186:187], v[150:151], v[16:17], v[186:187]
	v_pk_fma_f32 v[178:179], v[152:153], v[16:17], v[178:179]
	v_pk_fma_f32 v[170:171], v[156:157], v[16:17], v[170:171]
	v_pk_fma_f32 v[162:163], v[158:159], v[16:17], v[162:163]
	v_pk_fma_f32 v[154:155], v[160:161], v[16:17], v[154:155]
	v_pk_fma_f32 v[2:3], v[166:167], v[90:91], v[2:3]
	v_pk_fma_f32 v[240:241], v[144:145], v[96:97], v[240:241]
	v_pk_fma_f32 v[238:239], v[144:145], v[94:95], v[238:239]
	v_pk_fma_f32 v[236:237], v[142:143], v[94:95], v[236:237]
	v_pk_fma_f32 v[234:235], v[140:141], v[94:95], v[234:235]
	v_pk_fma_f32 v[232:233], v[138:139], v[94:95], v[232:233]
	v_pk_fma_f32 v[228:229], v[150:151], v[96:97], v[228:229]
	v_pk_fma_f32 v[230:231], v[150:151], v[94:95], v[230:231]
	v_lshlrev_b32_e32 v172, 16, v173
	v_and_b32_e32 v173, 0xffff0000, v173
	v_pk_fma_f32 v[196:197], v[150:151], v[92:93], v[196:197]
	v_pk_fma_f32 v[198:199], v[152:153], v[92:93], v[198:199]
	v_pk_fma_f32 v[186:187], v[152:153], v[90:91], v[186:187]
	v_pk_fma_f32 v[178:179], v[156:157], v[90:91], v[178:179]
	v_pk_fma_f32 v[170:171], v[158:159], v[90:91], v[170:171]
	v_pk_fma_f32 v[162:163], v[160:161], v[90:91], v[162:163]
	v_pk_fma_f32 v[154:155], v[164:165], v[90:91], v[154:155]
	v_pk_fma_f32 v[2:3], v[168:169], v[92:93], v[2:3]
	v_pk_fma_f32 v[240:241], v[142:143], v[98:99], v[240:241]
	v_pk_fma_f32 v[238:239], v[142:143], v[96:97], v[238:239]
	v_pk_fma_f32 v[236:237], v[140:141], v[96:97], v[236:237]
	v_pk_fma_f32 v[234:235], v[138:139], v[96:97], v[234:235]
	v_pk_fma_f32 v[232:233], v[146:147], v[96:97], v[232:233]
	v_pk_fma_f32 v[228:229], v[152:153], v[98:99], v[228:229]
	v_pk_fma_f32 v[230:231], v[152:153], v[96:97], v[230:231]
	v_lshlrev_b32_e32 v174, 16, v175
	v_and_b32_e32 v175, 0xffff0000, v175
	v_pk_fma_f32 v[196:197], v[152:153], v[94:95], v[196:197]
	v_pk_fma_f32 v[198:199], v[156:157], v[94:95], v[198:199]
	v_pk_fma_f32 v[186:187], v[156:157], v[92:93], v[186:187]
	v_pk_fma_f32 v[178:179], v[158:159], v[92:93], v[178:179]
	v_pk_fma_f32 v[170:171], v[160:161], v[92:93], v[170:171]
	v_pk_fma_f32 v[162:163], v[164:165], v[92:93], v[162:163]
	v_pk_fma_f32 v[154:155], v[166:167], v[92:93], v[154:155]
	v_pk_fma_f32 v[2:3], v[172:173], v[94:95], v[2:3]
	v_pk_fma_f32 v[242:243], v[142:143], v[100:101], v[242:243]
	v_pk_fma_f32 v[240:241], v[140:141], v[100:101], v[240:241]
	v_pk_fma_f32 v[238:239], v[140:141], v[98:99], v[238:239]
	v_pk_fma_f32 v[236:237], v[138:139], v[98:99], v[236:237]
	v_pk_fma_f32 v[234:235], v[146:147], v[98:99], v[234:235]
	v_pk_fma_f32 v[232:233], v[150:151], v[98:99], v[232:233]
	v_pk_fma_f32 v[228:229], v[156:157], v[100:101], v[228:229]
	v_pk_fma_f32 v[230:231], v[156:157], v[98:99], v[230:231]
	v_lshlrev_b32_e32 v176, 16, v177
	v_and_b32_e32 v177, 0xffff0000, v177
	v_pk_fma_f32 v[196:197], v[156:157], v[96:97], v[196:197]
	v_pk_fma_f32 v[198:199], v[158:159], v[96:97], v[198:199]
	v_pk_fma_f32 v[186:187], v[158:159], v[94:95], v[186:187]
	v_pk_fma_f32 v[178:179], v[160:161], v[94:95], v[178:179]
	v_pk_fma_f32 v[170:171], v[164:165], v[94:95], v[170:171]
	v_pk_fma_f32 v[162:163], v[166:167], v[94:95], v[162:163]
	v_pk_fma_f32 v[154:155], v[168:169], v[94:95], v[154:155]
	v_pk_fma_f32 v[2:3], v[174:175], v[96:97], v[2:3]
	v_pk_fma_f32 v[242:243], v[140:141], v[102:103], v[242:243]
	v_pk_fma_f32 v[240:241], v[138:139], v[102:103], v[240:241]
	v_pk_fma_f32 v[238:239], v[138:139], v[100:101], v[238:239]
	v_pk_fma_f32 v[236:237], v[146:147], v[100:101], v[236:237]
	v_pk_fma_f32 v[234:235], v[150:151], v[100:101], v[234:235]
	v_pk_fma_f32 v[232:233], v[152:153], v[100:101], v[232:233]
	v_pk_fma_f32 v[228:229], v[158:159], v[102:103], v[228:229]
	v_pk_fma_f32 v[230:231], v[158:159], v[100:101], v[230:231]
	v_pk_fma_f32 v[196:197], v[158:159], v[98:99], v[196:197]
	v_pk_fma_f32 v[198:199], v[160:161], v[98:99], v[198:199]
	v_pk_fma_f32 v[186:187], v[160:161], v[96:97], v[186:187]
	v_pk_fma_f32 v[178:179], v[164:165], v[96:97], v[178:179]
	v_pk_fma_f32 v[170:171], v[166:167], v[96:97], v[170:171]
	v_pk_fma_f32 v[162:163], v[168:169], v[96:97], v[162:163]
	v_pk_fma_f32 v[154:155], v[172:173], v[96:97], v[154:155]
	v_pk_fma_f32 v[2:3], v[176:177], v[98:99], v[2:3]
	v_pk_fma_f32 v[242:243], v[138:139], v[104:105], v[242:243]
	v_pk_fma_f32 v[240:241], v[146:147], v[104:105], v[240:241]
	v_pk_fma_f32 v[238:239], v[146:147], v[102:103], v[238:239]
	v_pk_fma_f32 v[236:237], v[150:151], v[102:103], v[236:237]
	v_pk_fma_f32 v[234:235], v[152:153], v[102:103], v[234:235]
	v_pk_fma_f32 v[232:233], v[156:157], v[102:103], v[232:233]
	v_pk_fma_f32 v[228:229], v[160:161], v[104:105], v[228:229]
	v_pk_fma_f32 v[230:231], v[160:161], v[102:103], v[230:231]
	v_pk_fma_f32 v[196:197], v[160:161], v[100:101], v[196:197]
	v_pk_fma_f32 v[198:199], v[164:165], v[100:101], v[198:199]
	v_pk_fma_f32 v[186:187], v[164:165], v[98:99], v[186:187]
	v_pk_fma_f32 v[178:179], v[166:167], v[98:99], v[178:179]
	v_pk_fma_f32 v[170:171], v[168:169], v[98:99], v[170:171]
	v_pk_fma_f32 v[162:163], v[172:173], v[98:99], v[162:163]
	v_pk_fma_f32 v[154:155], v[174:175], v[98:99], v[154:155]
	v_pk_fma_f32 v[2:3], v[180:181], v[100:101], v[2:3]
	v_pk_fma_f32 v[242:243], v[146:147], v[106:107], v[242:243]
	v_pk_fma_f32 v[240:241], v[150:151], v[106:107], v[240:241]
	v_pk_fma_f32 v[238:239], v[150:151], v[104:105], v[238:239]
	v_pk_fma_f32 v[236:237], v[152:153], v[104:105], v[236:237]
	v_pk_fma_f32 v[234:235], v[156:157], v[104:105], v[234:235]
	v_pk_fma_f32 v[232:233], v[158:159], v[104:105], v[232:233]
	v_pk_fma_f32 v[228:229], v[164:165], v[106:107], v[228:229]
	v_pk_fma_f32 v[230:231], v[164:165], v[104:105], v[230:231]
	v_pk_fma_f32 v[196:197], v[164:165], v[102:103], v[196:197]
	v_pk_fma_f32 v[198:199], v[166:167], v[102:103], v[198:199]
	v_pk_fma_f32 v[186:187], v[166:167], v[100:101], v[186:187]
	v_pk_fma_f32 v[178:179], v[168:169], v[100:101], v[178:179]
	v_pk_fma_f32 v[170:171], v[172:173], v[100:101], v[170:171]
	v_pk_fma_f32 v[162:163], v[174:175], v[100:101], v[162:163]
	v_pk_fma_f32 v[154:155], v[176:177], v[100:101], v[154:155]
	v_pk_fma_f32 v[2:3], v[182:183], v[102:103], v[2:3]
	v_pk_fma_f32 v[242:243], v[150:151], v[108:109], v[242:243]
	v_pk_fma_f32 v[240:241], v[152:153], v[108:109], v[240:241]
	v_pk_fma_f32 v[238:239], v[152:153], v[106:107], v[238:239]
	v_pk_fma_f32 v[236:237], v[156:157], v[106:107], v[236:237]
	v_pk_fma_f32 v[234:235], v[158:159], v[106:107], v[234:235]
	v_pk_fma_f32 v[232:233], v[160:161], v[106:107], v[232:233]
	v_pk_fma_f32 v[228:229], v[166:167], v[108:109], v[228:229]
	v_add_u32_e32 v146, v215, v226
	v_add_u32_e32 v146, 0x2000, v146
	v_ashrrev_i32_e32 v147, 31, v146
	v_lshlrev_b64 v[144:145], 10, v[146:147]
	v_lshl_add_u64 v[144:145], v[86:87], 0, v[144:145]
	global_load_dwordx2 v[128:129], v[144:145], off
	global_load_dwordx2 v[130:131], v[144:145], off offset:512
	global_load_dwordx2 v[132:133], v[144:145], off offset:1024
	global_load_dwordx2 v[134:135], v[144:145], off offset:1536
	global_load_dwordx2 v[136:137], v[144:145], off offset:2048
	global_load_dwordx2 v[138:139], v[144:145], off offset:2560
	global_load_dwordx2 v[140:141], v[144:145], off offset:3072
	global_load_dwordx2 v[142:143], v[144:145], off offset:3584
	v_pk_fma_f32 v[230:231], v[166:167], v[106:107], v[230:231]
	v_pk_fma_f32 v[196:197], v[166:167], v[104:105], v[196:197]
	v_pk_fma_f32 v[198:199], v[168:169], v[104:105], v[198:199]
	v_pk_fma_f32 v[186:187], v[168:169], v[102:103], v[186:187]
	v_pk_fma_f32 v[178:179], v[172:173], v[102:103], v[178:179]
	v_pk_fma_f32 v[170:171], v[174:175], v[102:103], v[170:171]
	v_pk_fma_f32 v[162:163], v[176:177], v[102:103], v[162:163]
	v_pk_fma_f32 v[154:155], v[180:181], v[102:103], v[154:155]
	v_pk_fma_f32 v[2:3], v[184:185], v[104:105], v[2:3]
	v_pk_fma_f32 v[242:243], v[152:153], v[110:111], v[242:243]
	v_pk_fma_f32 v[240:241], v[156:157], v[110:111], v[240:241]
	v_pk_fma_f32 v[238:239], v[156:157], v[108:109], v[238:239]
	v_pk_fma_f32 v[236:237], v[158:159], v[108:109], v[236:237]
	v_pk_fma_f32 v[234:235], v[160:161], v[108:109], v[234:235]
	v_pk_fma_f32 v[232:233], v[164:165], v[108:109], v[232:233]
	v_pk_fma_f32 v[228:229], v[168:169], v[110:111], v[228:229]
	v_pk_fma_f32 v[230:231], v[168:169], v[108:109], v[230:231]
	v_pk_fma_f32 v[196:197], v[168:169], v[106:107], v[196:197]
	v_pk_fma_f32 v[198:199], v[172:173], v[106:107], v[198:199]
	v_pk_fma_f32 v[186:187], v[172:173], v[104:105], v[186:187]
	v_pk_fma_f32 v[178:179], v[174:175], v[104:105], v[178:179]
	v_pk_fma_f32 v[170:171], v[176:177], v[104:105], v[170:171]
	v_pk_fma_f32 v[162:163], v[180:181], v[104:105], v[162:163]
	v_pk_fma_f32 v[154:155], v[182:183], v[104:105], v[154:155]
	v_pk_fma_f32 v[2:3], v[188:189], v[106:107], v[2:3]
	v_pk_fma_f32 v[242:243], v[156:157], v[112:113], v[242:243]
	v_pk_fma_f32 v[240:241], v[158:159], v[112:113], v[240:241]
	v_pk_fma_f32 v[238:239], v[158:159], v[110:111], v[238:239]
	v_pk_fma_f32 v[236:237], v[160:161], v[110:111], v[236:237]
	v_pk_fma_f32 v[234:235], v[164:165], v[110:111], v[234:235]
	v_pk_fma_f32 v[232:233], v[166:167], v[110:111], v[232:233]
	v_pk_fma_f32 v[228:229], v[172:173], v[112:113], v[228:229]
	v_pk_fma_f32 v[230:231], v[172:173], v[110:111], v[230:231]
	v_pk_fma_f32 v[196:197], v[172:173], v[108:109], v[196:197]
	v_pk_fma_f32 v[198:199], v[174:175], v[108:109], v[198:199]
	v_pk_fma_f32 v[186:187], v[174:175], v[106:107], v[186:187]
	v_pk_fma_f32 v[178:179], v[176:177], v[106:107], v[178:179]
	v_pk_fma_f32 v[170:171], v[180:181], v[106:107], v[170:171]
	v_pk_fma_f32 v[162:163], v[182:183], v[106:107], v[162:163]
	v_pk_fma_f32 v[154:155], v[184:185], v[106:107], v[154:155]
	v_pk_fma_f32 v[2:3], v[190:191], v[108:109], v[2:3]
	v_pk_fma_f32 v[242:243], v[158:159], v[114:115], v[242:243]
	v_pk_fma_f32 v[240:241], v[160:161], v[114:115], v[240:241]
	v_pk_fma_f32 v[238:239], v[160:161], v[112:113], v[238:239]
	v_pk_fma_f32 v[236:237], v[164:165], v[112:113], v[236:237]
	v_pk_fma_f32 v[234:235], v[166:167], v[112:113], v[234:235]
	v_pk_fma_f32 v[232:233], v[168:169], v[112:113], v[232:233]
	v_pk_fma_f32 v[228:229], v[174:175], v[114:115], v[228:229]
	v_pk_fma_f32 v[230:231], v[174:175], v[112:113], v[230:231]
	v_pk_fma_f32 v[196:197], v[174:175], v[110:111], v[196:197]
	v_pk_fma_f32 v[198:199], v[176:177], v[110:111], v[198:199]
	v_pk_fma_f32 v[186:187], v[176:177], v[108:109], v[186:187]
	v_pk_fma_f32 v[178:179], v[180:181], v[108:109], v[178:179]
	v_pk_fma_f32 v[170:171], v[182:183], v[108:109], v[170:171]
	v_pk_fma_f32 v[162:163], v[184:185], v[108:109], v[162:163]
	v_pk_fma_f32 v[154:155], v[188:189], v[108:109], v[154:155]
	v_pk_fma_f32 v[2:3], v[192:193], v[110:111], v[2:3]
	v_pk_fma_f32 v[242:243], v[160:161], v[116:117], v[242:243]
	v_pk_fma_f32 v[240:241], v[164:165], v[116:117], v[240:241]
	v_pk_fma_f32 v[238:239], v[164:165], v[114:115], v[238:239]
	v_pk_fma_f32 v[236:237], v[166:167], v[114:115], v[236:237]
	v_pk_fma_f32 v[234:235], v[168:169], v[114:115], v[234:235]
	v_pk_fma_f32 v[232:233], v[172:173], v[114:115], v[232:233]
	v_pk_fma_f32 v[228:229], v[176:177], v[116:117], v[228:229]
	v_pk_fma_f32 v[230:231], v[176:177], v[114:115], v[230:231]
	v_pk_fma_f32 v[196:197], v[176:177], v[112:113], v[196:197]
	v_pk_fma_f32 v[198:199], v[180:181], v[112:113], v[198:199]
	v_pk_fma_f32 v[186:187], v[180:181], v[110:111], v[186:187]
	v_pk_fma_f32 v[178:179], v[182:183], v[110:111], v[178:179]
	v_pk_fma_f32 v[170:171], v[184:185], v[110:111], v[170:171]
	v_pk_fma_f32 v[162:163], v[188:189], v[110:111], v[162:163]
	v_pk_fma_f32 v[154:155], v[190:191], v[110:111], v[154:155]
	v_pk_fma_f32 v[2:3], v[194:195], v[112:113], v[2:3]
	v_pk_fma_f32 v[242:243], v[164:165], v[118:119], v[242:243]
	v_pk_fma_f32 v[240:241], v[166:167], v[118:119], v[240:241]
	v_pk_fma_f32 v[238:239], v[166:167], v[116:117], v[238:239]
	v_pk_fma_f32 v[236:237], v[168:169], v[116:117], v[236:237]
	v_pk_fma_f32 v[234:235], v[172:173], v[116:117], v[234:235]
	v_pk_fma_f32 v[232:233], v[174:175], v[116:117], v[232:233]
	v_pk_fma_f32 v[228:229], v[180:181], v[118:119], v[228:229]
	v_pk_fma_f32 v[230:231], v[180:181], v[116:117], v[230:231]
	v_pk_fma_f32 v[196:197], v[180:181], v[114:115], v[196:197]
	v_pk_fma_f32 v[198:199], v[182:183], v[114:115], v[198:199]
	v_pk_fma_f32 v[186:187], v[182:183], v[112:113], v[186:187]
	v_pk_fma_f32 v[178:179], v[184:185], v[112:113], v[178:179]
	v_pk_fma_f32 v[170:171], v[188:189], v[112:113], v[170:171]
	v_pk_fma_f32 v[162:163], v[190:191], v[112:113], v[162:163]
	v_pk_fma_f32 v[154:155], v[192:193], v[112:113], v[154:155]
	v_pk_fma_f32 v[2:3], v[200:201], v[114:115], v[2:3]
	v_pk_fma_f32 v[242:243], v[166:167], v[120:121], v[242:243]
	v_pk_fma_f32 v[240:241], v[168:169], v[120:121], v[240:241]
	v_pk_fma_f32 v[238:239], v[168:169], v[118:119], v[238:239]
	v_pk_fma_f32 v[236:237], v[172:173], v[118:119], v[236:237]
	v_pk_fma_f32 v[234:235], v[174:175], v[118:119], v[234:235]
	v_pk_fma_f32 v[232:233], v[176:177], v[118:119], v[232:233]
	v_pk_fma_f32 v[228:229], v[182:183], v[120:121], v[228:229]
	v_pk_fma_f32 v[230:231], v[182:183], v[118:119], v[230:231]
	v_pk_fma_f32 v[196:197], v[182:183], v[116:117], v[196:197]
	v_pk_fma_f32 v[198:199], v[184:185], v[116:117], v[198:199]
	v_pk_fma_f32 v[186:187], v[184:185], v[114:115], v[186:187]
	v_pk_fma_f32 v[178:179], v[188:189], v[114:115], v[178:179]
	v_pk_fma_f32 v[170:171], v[190:191], v[114:115], v[170:171]
	v_pk_fma_f32 v[162:163], v[192:193], v[114:115], v[162:163]
	v_pk_fma_f32 v[154:155], v[194:195], v[114:115], v[154:155]
	v_pk_fma_f32 v[2:3], v[202:203], v[116:117], v[2:3]
	v_pk_fma_f32 v[242:243], v[168:169], v[122:123], v[242:243]
	v_pk_fma_f32 v[240:241], v[172:173], v[122:123], v[240:241]
	v_pk_fma_f32 v[238:239], v[172:173], v[120:121], v[238:239]
	v_pk_fma_f32 v[236:237], v[174:175], v[120:121], v[236:237]
	v_pk_fma_f32 v[234:235], v[176:177], v[120:121], v[234:235]
	v_pk_fma_f32 v[232:233], v[180:181], v[120:121], v[232:233]
	v_pk_fma_f32 v[228:229], v[184:185], v[122:123], v[228:229]
	v_pk_fma_f32 v[230:231], v[184:185], v[120:121], v[230:231]
	v_pk_fma_f32 v[196:197], v[184:185], v[118:119], v[196:197]
	v_pk_fma_f32 v[198:199], v[188:189], v[118:119], v[198:199]
	v_pk_fma_f32 v[186:187], v[188:189], v[116:117], v[186:187]
	v_pk_fma_f32 v[178:179], v[190:191], v[116:117], v[178:179]
	v_lshlrev_b32_e32 v206, 16, v207
	v_and_b32_e32 v207, 0xffff0000, v207
	v_pk_fma_f32 v[170:171], v[192:193], v[116:117], v[170:171]
	v_pk_fma_f32 v[162:163], v[194:195], v[116:117], v[162:163]
	v_pk_fma_f32 v[154:155], v[200:201], v[116:117], v[154:155]
	v_pk_fma_f32 v[2:3], v[204:205], v[118:119], v[2:3]
	v_pk_fma_f32 v[242:243], v[172:173], v[124:125], v[242:243]
	v_pk_fma_f32 v[240:241], v[174:175], v[124:125], v[240:241]
	v_pk_fma_f32 v[238:239], v[174:175], v[122:123], v[238:239]
	v_pk_fma_f32 v[236:237], v[176:177], v[122:123], v[236:237]
	v_pk_fma_f32 v[234:235], v[180:181], v[122:123], v[234:235]
	v_pk_fma_f32 v[232:233], v[182:183], v[122:123], v[232:233]
	v_pk_fma_f32 v[228:229], v[188:189], v[124:125], v[228:229]
	v_pk_fma_f32 v[230:231], v[188:189], v[122:123], v[230:231]
	v_pk_fma_f32 v[196:197], v[188:189], v[120:121], v[196:197]
	v_pk_fma_f32 v[198:199], v[190:191], v[120:121], v[198:199]
	v_pk_fma_f32 v[186:187], v[190:191], v[118:119], v[186:187]
	v_pk_fma_f32 v[178:179], v[192:193], v[118:119], v[178:179]
	v_pk_fma_f32 v[170:171], v[194:195], v[118:119], v[170:171]
	v_lshlrev_b32_e32 v208, 16, v209
	v_and_b32_e32 v209, 0xffff0000, v209
	v_pk_fma_f32 v[162:163], v[200:201], v[118:119], v[162:163]
	v_pk_fma_f32 v[154:155], v[202:203], v[118:119], v[154:155]
	v_pk_fma_f32 v[2:3], v[206:207], v[120:121], v[2:3]
	v_pk_fma_f32 v[242:243], v[174:175], v[126:127], v[242:243]
	v_pk_fma_f32 v[240:241], v[176:177], v[126:127], v[240:241]
	v_pk_fma_f32 v[238:239], v[176:177], v[124:125], v[238:239]
	v_pk_fma_f32 v[236:237], v[180:181], v[124:125], v[236:237]
	v_pk_fma_f32 v[234:235], v[182:183], v[124:125], v[234:235]
	v_pk_fma_f32 v[232:233], v[184:185], v[124:125], v[232:233]
	v_pk_fma_f32 v[228:229], v[190:191], v[126:127], v[228:229]
	v_pk_fma_f32 v[230:231], v[190:191], v[124:125], v[230:231]
	v_pk_fma_f32 v[196:197], v[190:191], v[122:123], v[196:197]
	v_pk_fma_f32 v[198:199], v[192:193], v[122:123], v[198:199]
	v_pk_fma_f32 v[186:187], v[192:193], v[120:121], v[186:187]
	v_pk_fma_f32 v[178:179], v[194:195], v[120:121], v[178:179]
	v_pk_fma_f32 v[170:171], v[200:201], v[120:121], v[170:171]
	v_pk_fma_f32 v[162:163], v[202:203], v[120:121], v[162:163]
	v_lshlrev_b32_e32 v210, 16, v211
	v_and_b32_e32 v211, 0xffff0000, v211
	v_pk_fma_f32 v[154:155], v[204:205], v[120:121], v[154:155]
	v_pk_fma_f32 v[2:3], v[208:209], v[122:123], v[2:3]
	v_add_u32_e32 v120, v215, v226
	v_pk_fma_f32 v[238:239], v[180:181], v[126:127], v[238:239]
	v_pk_fma_f32 v[236:237], v[182:183], v[126:127], v[236:237]
	v_pk_fma_f32 v[234:235], v[184:185], v[126:127], v[234:235]
	v_pk_fma_f32 v[232:233], v[188:189], v[126:127], v[232:233]
	v_pk_fma_f32 v[230:231], v[192:193], v[126:127], v[230:231]
	ds_write2st64_b64 v214, v[242:243], v[240:241] offset1:4
	ds_write2st64_b64 v214, v[238:239], v[236:237] offset0:8 offset1:12
	ds_write2st64_b64 v214, v[234:235], v[232:233] offset0:16 offset1:20
	ds_write2st64_b64 v214, v[228:229], v[230:231] offset0:24 offset1:28
	v_pk_fma_f32 v[196:197], v[192:193], v[124:125], v[196:197]
	v_pk_fma_f32 v[198:199], v[194:195], v[124:125], v[198:199]
	v_pk_fma_f32 v[186:187], v[194:195], v[122:123], v[186:187]
	v_pk_fma_f32 v[178:179], v[200:201], v[122:123], v[178:179]
	v_pk_fma_f32 v[170:171], v[202:203], v[122:123], v[170:171]
	v_pk_fma_f32 v[162:163], v[204:205], v[122:123], v[162:163]
	v_pk_fma_f32 v[154:155], v[206:207], v[122:123], v[154:155]
	v_lshlrev_b32_e32 v228, 16, v227
	v_and_b32_e32 v229, 0xffff0000, v227
	v_pk_fma_f32 v[2:3], v[210:211], v[124:125], v[2:3]
	v_add_u32_e32 v98, 0x2000, v120
	v_pk_fma_f32 v[196:197], v[194:195], v[126:127], v[196:197]
	v_pk_fma_f32 v[198:199], v[200:201], v[126:127], v[198:199]
	v_pk_fma_f32 v[186:187], v[200:201], v[124:125], v[186:187]
	v_pk_fma_f32 v[178:179], v[202:203], v[124:125], v[178:179]
	v_pk_fma_f32 v[170:171], v[204:205], v[124:125], v[170:171]
	v_pk_fma_f32 v[162:163], v[206:207], v[124:125], v[162:163]
	v_pk_fma_f32 v[154:155], v[208:209], v[124:125], v[154:155]
	v_pk_fma_f32 v[2:3], v[228:229], v[126:127], v[2:3]
	v_ashrrev_i32_e32 v99, 31, v98
	v_pk_fma_f32 v[186:187], v[202:203], v[126:127], v[186:187]
	v_pk_fma_f32 v[178:179], v[204:205], v[126:127], v[178:179]
	v_pk_fma_f32 v[170:171], v[206:207], v[126:127], v[170:171]
	v_pk_fma_f32 v[162:163], v[208:209], v[126:127], v[162:163]
	v_pk_fma_f32 v[154:155], v[210:211], v[126:127], v[154:155]
	ds_write2st64_b64 v214, v[196:197], v[198:199] offset0:32 offset1:36
	ds_write2st64_b64 v214, v[186:187], v[178:179] offset0:40 offset1:44
	ds_write2st64_b64 v214, v[170:171], v[162:163] offset0:48 offset1:52
	ds_write2st64_b64 v214, v[154:155], v[2:3] offset0:56 offset1:60
	v_lshlrev_b64 v[2:3], 10, v[98:99]
	v_lshl_add_u64 v[2:3], v[86:87], 0, v[2:3]
	s_waitcnt lgkmcnt(0)
	s_barrier
	v_add_u32_e32 v226, s9, v226
	s_waitcnt vmcnt(7)
	v_lshlrev_b32_e32 v100, 16, v128
	v_and_b32_e32 v101, 0xffff0000, v128
	v_lshlrev_b32_e32 v102, 16, v129
	v_and_b32_e32 v103, 0xffff0000, v129
	s_waitcnt vmcnt(6)
	v_lshlrev_b32_e32 v104, 16, v130
	v_and_b32_e32 v105, 0xffff0000, v130
	v_lshlrev_b32_e32 v106, 16, v131
	v_and_b32_e32 v107, 0xffff0000, v131
	global_load_dwordx4 v[2:5], v[82:83], off offset:1024
	global_load_dwordx4 v[6:9], v[84:85], off offset:1024
	ds_read_b128 v[90:93], v216 offset:1024
	global_load_dwordx4 v[10:13], v[82:83], off
	global_load_dwordx4 v[14:17], v[84:85], off
	ds_read_b128 v[94:97], v216
	s_waitcnt lgkmcnt(1)
	v_pk_mul_f32 v[110:111], v[90:91], v[90:91]
	v_pk_mul_f32 v[108:109], v[92:93], v[92:93]
	s_waitcnt lgkmcnt(0)
	v_mov_b32_e32 v114, v94
	v_mov_b32_e32 v115, v96
	v_pk_mul_f32 v[114:115], v[114:115], v[114:115]
	v_pk_mul_f32 v[116:117], v[94:95], v[94:95]
	v_mov_b32_e32 v118, v114
	v_mov_b32_e32 v119, v94
	v_mov_b32_e32 v116, v117
	v_mov_b32_e32 v117, v95
	v_pk_mul_f32 v[112:113], v[96:97], v[96:97]
	v_pk_add_f32 v[116:117], v[118:119], v[116:117]
	v_pk_mov_b32 v[114:115], v[114:115], v[96:97] op_sel:[1,0]
	v_mov_b32_e32 v112, v113
	v_pk_add_f32 v[114:115], v[116:117], v[114:115]
	v_mov_b32_e32 v113, v97
	v_pk_add_f32 v[112:113], v[114:115], v[112:113]
	v_mov_b32_e32 v114, v110
	v_mov_b32_e32 v115, v90
	v_pk_add_f32 v[112:113], v[112:113], v[114:115]
	v_mov_b32_e32 v110, v111
	v_mov_b32_e32 v111, v91
	v_pk_add_f32 v[110:111], v[112:113], v[110:111]
	v_mov_b32_e32 v112, v108
	v_mov_b32_e32 v113, v92
	v_pk_add_f32 v[110:111], v[110:111], v[112:113]
	v_mov_b32_e32 v108, v109
	v_mov_b32_e32 v109, v93
	v_pk_add_f32 v[108:109], v[110:111], v[108:109]
	ds_bpermute_b32 v111, v217, v109
	ds_bpermute_b32 v110, v217, v108
	s_waitcnt lgkmcnt(0)
	v_pk_add_f32 v[108:109], v[108:109], v[110:111]
	ds_bpermute_b32 v111, v218, v109
	ds_bpermute_b32 v110, v218, v108
	s_waitcnt lgkmcnt(0)
	v_pk_add_f32 v[108:109], v[108:109], v[110:111]
	ds_bpermute_b32 v111, v219, v109
	ds_bpermute_b32 v110, v219, v108
	s_waitcnt lgkmcnt(0)
	v_pk_add_f32 v[108:109], v[108:109], v[110:111]
	ds_bpermute_b32 v111, v220, v109
	ds_bpermute_b32 v110, v220, v108
	s_waitcnt lgkmcnt(0)
	v_pk_add_f32 v[108:109], v[108:109], v[110:111]
	ds_bpermute_b32 v111, v221, v109
	ds_bpermute_b32 v110, v221, v108
	s_waitcnt lgkmcnt(0)
	v_pk_add_f32 v[108:109], v[108:109], v[110:111]
	ds_bpermute_b32 v111, v222, v109
	ds_bpermute_b32 v110, v222, v108
	s_waitcnt lgkmcnt(0)
	v_pk_add_f32 v[108:109], v[108:109], v[110:111]
	s_nop 0
	v_pk_mul_f32 v[108:109], v[108:109], s[6:7] op_sel_hi:[1,0]
	s_nop 0
	v_fma_f32 v110, -v109, v109, v108
	v_max_f32_e32 v110, 0, v110
	v_add_f32_e32 v110, 0x358637bd, v110
	v_cmp_gt_f32_e32 vcc, s22, v110
	v_mul_f32_e32 v111, 0x4b800000, v110
	v_pk_add_f32 v[94:95], v[94:95], v[108:109] op_sel:[0,1] neg_lo:[0,1] neg_hi:[0,1]
	v_cndmask_b32_e32 v110, v110, v111, vcc
	v_rsq_f32_e32 v110, v110
	v_pk_add_f32 v[96:97], v[96:97], v[108:109] op_sel:[0,1] neg_lo:[0,1] neg_hi:[0,1]
	v_pk_add_f32 v[90:91], v[90:91], v[108:109] op_sel:[0,1] neg_lo:[0,1] neg_hi:[0,1]
	v_pk_add_f32 v[92:93], v[92:93], v[108:109] op_sel:[0,1] neg_lo:[0,1] neg_hi:[0,1]
	v_mul_f32_e32 v111, 0x45800000, v110
	v_cndmask_b32_e32 v110, v110, v111, vcc
	v_pk_mul_f32 v[94:95], v[94:95], v[110:111] op_sel_hi:[1,0]
	s_waitcnt vmcnt(0)
	v_cmp_ge_i32_e64 s[98:99], s23, v1
	s_nop 0
	s_and_b64 s[98:99], s[98:99], exec
	s_cbranch_scc0 .Lcpf_skip_nxt
	v_lshrrev_b32_e32 v253, 12, v226
	v_cmp_gt_i32_e64 s[98:99], s10, v1
	v_lshrrev_b32_e32 v252, 4, v1
	v_add_u32_e32 v253, 32, v253
	v_cndmask_b32_e64 v252, v253, v252, s[98:99]
	v_lshlrev_b32_e32 v252, 5, v252
	v_add3_u32 v252, v226, v252, s11
	v_ashrrev_i32_e32 v253, 31, v252
	v_lshlrev_b64 v[252:253], 10, v[252:253]
	v_lshl_add_u64 v[252:253], v[78:79], 0, v[252:253]
	s_mov_b64 s[100:101], 0x1000
	v_lshl_add_u64 v[252:253], v[252:253], 0, s[100:101]
	s_mov_b64 s[100:101], 0x2000
	global_load_dword v146, v[252:253], off offset:-4096
	global_load_dword v145, v[252:253], off offset:-3072
	global_load_dword v150, v[252:253], off offset:-2048
	global_load_dword v152, v[252:253], off offset:-1024
	global_load_dword v156, v[252:253], off
	global_load_dword v158, v[252:253], off offset:1024
	global_load_dword v160, v[252:253], off offset:2048
	global_load_dword v164, v[252:253], off offset:3072
	v_lshl_add_u64 v[252:253], v[252:253], 0, s[100:101]
	global_load_dword v166, v[252:253], off offset:-4096
	global_load_dword v168, v[252:253], off offset:-3072
	global_load_dword v172, v[252:253], off offset:-2048
	global_load_dword v174, v[252:253], off offset:-1024
	global_load_dword v176, v[252:253], off
	global_load_dword v144, v[252:253], off offset:1024
	global_load_dword v251, v[252:253], off offset:2048
	global_load_dword v250, v[252:253], off offset:3072
	v_lshl_add_u64 v[252:253], v[252:253], 0, s[100:101]
	global_load_dword v249, v[252:253], off offset:-4096
	global_load_dword v248, v[252:253], off offset:-3072
	global_load_dword v246, v[252:253], off offset:-2048
	global_load_dword v247, v[252:253], off offset:-1024
	global_load_dword v147, v[252:253], off
	global_load_dword v151, v[252:253], off offset:1024
	global_load_dword v153, v[252:253], off offset:2048
	global_load_dword v157, v[252:253], off offset:3072
	v_lshl_add_u64 v[252:253], v[252:253], 0, s[100:101]
	global_load_dword v159, v[252:253], off offset:-4096
	global_load_dword v161, v[252:253], off offset:-3072
	global_load_dword v165, v[252:253], off offset:-2048
	global_load_dword v167, v[252:253], off offset:-1024
	global_load_dword v169, v[252:253], off
	global_load_dword v173, v[252:253], off offset:1024
	global_load_dword v175, v[252:253], off offset:2048
	global_load_dword v177, v[252:253], off offset:3072
	v_lshl_add_u64 v[252:253], v[252:253], 0, s[100:101]
	global_load_dword v181, v[252:253], off offset:-4096
	global_load_dword v183, v[252:253], off offset:-3072
	global_load_dword v185, v[252:253], off offset:-2048
	global_load_dword v189, v[252:253], off offset:-1024
	global_load_dword v191, v[252:253], off
	global_load_dword v193, v[252:253], off offset:1024
	global_load_dword v195, v[252:253], off offset:2048
	global_load_dword v201, v[252:253], off offset:3072
	v_lshl_add_u64 v[252:253], v[252:253], 0, s[100:101]
	global_load_dword v203, v[252:253], off offset:-4096
	global_load_dword v205, v[252:253], off offset:-3072
	global_load_dword v207, v[252:253], off offset:-2048
	global_load_dword v209, v[252:253], off offset:-1024
	global_load_dword v211, v[252:253], off
	global_load_dword v227, v[252:253], off offset:1024
.Lcpf_skip_nxt:
	v_pk_fma_f32 v[94:95], v[10:11], v[94:95], v[14:15]
	s_nop 0
	v_mul_f32_e32 v111, 0xbfb8aa3b, v94
	v_exp_f32_e32 v111, v111
	s_nop 0
	v_add_f32_e32 v111, 1.0, v111
	v_rcp_f32_e32 v112, v111
	v_mul_f32_e32 v111, 0xbfb8aa3b, v95
	v_exp_f32_e32 v111, v111
	s_nop 0
	v_add_f32_e32 v111, 1.0, v111
	v_rcp_f32_e32 v113, v111
	v_pk_mul_f32 v[96:97], v[96:97], v[110:111] op_sel_hi:[1,0]
	v_pk_mul_f32 v[90:91], v[90:91], v[110:111] op_sel_hi:[1,0]
	v_pk_fma_f32 v[96:97], v[12:13], v[96:97], v[16:17]
	v_pk_mul_f32 v[94:95], v[94:95], v[112:113]
	v_pk_fma_f32 v[90:91], v[2:3], v[90:91], v[6:7]
	v_pk_mul_f32 v[94:95], v[94:95], v[100:101]
	v_pk_mul_f32 v[92:93], v[92:93], v[110:111] op_sel_hi:[1,0]
	v_cvt_pk_bf16_f32 v94, v94, v95
	v_mul_f32_e32 v95, 0xbfb8aa3b, v96
	v_exp_f32_e32 v95, v95
	v_pk_fma_f32 v[92:93], v[4:5], v[92:93], v[8:9]
	v_add_f32_e32 v95, 1.0, v95
	v_rcp_f32_e32 v100, v95
	v_mul_f32_e32 v95, 0xbfb8aa3b, v97
	v_exp_f32_e32 v95, v95
	s_nop 0
	v_add_f32_e32 v95, 1.0, v95
	v_rcp_f32_e32 v101, v95
	s_nop 0
	v_pk_mul_f32 v[96:97], v[96:97], v[100:101]
	s_nop 0
	v_pk_mul_f32 v[96:97], v[96:97], v[102:103]
	s_nop 0
	v_cvt_pk_bf16_f32 v95, v96, v97
	v_mul_f32_e32 v96, 0xbfb8aa3b, v90
	v_mul_f32_e32 v97, 0xbfb8aa3b, v91
	v_exp_f32_e32 v96, v96
	v_exp_f32_e32 v97, v97
	v_add_f32_e32 v96, 1.0, v96
	v_add_f32_e32 v97, 1.0, v97
	v_rcp_f32_e32 v96, v96
	v_rcp_f32_e32 v97, v97
	s_nop 0
	v_pk_mul_f32 v[90:91], v[90:91], v[96:97]
	s_nop 0
	v_pk_mul_f32 v[90:91], v[90:91], v[104:105]
	s_nop 0
	v_cvt_pk_bf16_f32 v90, v90, v91
	v_mul_f32_e32 v91, 0xbfb8aa3b, v92
	v_exp_f32_e32 v91, v91
	s_nop 0
	v_add_f32_e32 v91, 1.0, v91
	v_rcp_f32_e32 v96, v91
	v_mul_f32_e32 v91, 0xbfb8aa3b, v93
	v_exp_f32_e32 v91, v91
	s_nop 0
	v_add_f32_e32 v91, 1.0, v91
	v_rcp_f32_e32 v97, v91
	s_nop 0
	v_pk_mul_f32 v[92:93], v[92:93], v[96:97]
	s_nop 0
	v_pk_mul_f32 v[92:93], v[92:93], v[106:107]
	s_nop 0
	v_cvt_pk_bf16_f32 v91, v92, v93
	v_lshlrev_b64 v[92:93], 11, v[98:99]
	v_add_u32_e32 v98, 0x2001, v120
	v_lshl_add_u64 v[92:93], v[88:89], 0, v[92:93]
	v_ashrrev_i32_e32 v99, 31, v98
	global_store_dwordx2 v[92:93], v[94:95], off
	global_store_dwordx2 v[92:93], v[90:91], off offset:512
	v_lshlrev_b64 v[90:91], 10, v[98:99]
	v_lshl_add_u64 v[90:91], v[86:87], 0, v[90:91]
	ds_read_b128 v[94:97], v223
	s_waitcnt lgkmcnt(0)
	v_mov_b32_e32 v114, v94
	v_mov_b32_e32 v115, v96
	v_pk_mul_f32 v[114:115], v[114:115], v[114:115]
	v_pk_mul_f32 v[116:117], v[94:95], v[94:95]
	v_mov_b32_e32 v118, v114
	v_mov_b32_e32 v119, v94
	v_mov_b32_e32 v116, v117
	v_mov_b32_e32 v117, v95
	v_pk_mul_f32 v[112:113], v[96:97], v[96:97]
	v_pk_add_f32 v[116:117], v[118:119], v[116:117]
	v_pk_mov_b32 v[114:115], v[114:115], v[96:97] op_sel:[1,0]
	v_mov_b32_e32 v112, v113
	v_pk_add_f32 v[114:115], v[116:117], v[114:115]
	v_mov_b32_e32 v113, v97
	v_pk_add_f32 v[112:113], v[114:115], v[112:113]
	v_lshlrev_b32_e32 v100, 16, v132
	v_and_b32_e32 v101, 0xffff0000, v132
	v_lshlrev_b32_e32 v102, 16, v133
	v_and_b32_e32 v103, 0xffff0000, v133
	v_lshlrev_b32_e32 v104, 16, v134
	v_and_b32_e32 v105, 0xffff0000, v134
	v_lshlrev_b32_e32 v106, 16, v135
	v_and_b32_e32 v107, 0xffff0000, v135
	ds_read_b128 v[90:93], v223 offset:1024
	s_waitcnt lgkmcnt(0)
	v_pk_mul_f32 v[110:111], v[90:91], v[90:91]
	s_nop 0
	v_mov_b32_e32 v114, v110
	v_mov_b32_e32 v115, v90
	v_pk_mul_f32 v[108:109], v[92:93], v[92:93]
	v_pk_add_f32 v[112:113], v[112:113], v[114:115]
	v_mov_b32_e32 v110, v111
	v_mov_b32_e32 v111, v91
	v_pk_add_f32 v[110:111], v[112:113], v[110:111]
	v_mov_b32_e32 v112, v108
	v_mov_b32_e32 v113, v92
	v_pk_add_f32 v[110:111], v[110:111], v[112:113]
	v_mov_b32_e32 v108, v109
	v_mov_b32_e32 v109, v93
	v_pk_add_f32 v[108:109], v[110:111], v[108:109]
	ds_bpermute_b32 v111, v217, v109
	ds_bpermute_b32 v110, v217, v108
	s_waitcnt lgkmcnt(0)
	v_pk_add_f32 v[108:109], v[108:109], v[110:111]
	ds_bpermute_b32 v111, v218, v109
	ds_bpermute_b32 v110, v218, v108
	s_waitcnt lgkmcnt(0)
	v_pk_add_f32 v[108:109], v[108:109], v[110:111]
	ds_bpermute_b32 v111, v219, v109
	ds_bpermute_b32 v110, v219, v108
	s_waitcnt lgkmcnt(0)
	v_pk_add_f32 v[108:109], v[108:109], v[110:111]
	ds_bpermute_b32 v111, v220, v109
	ds_bpermute_b32 v110, v220, v108
	s_waitcnt lgkmcnt(0)
	v_pk_add_f32 v[108:109], v[108:109], v[110:111]
	ds_bpermute_b32 v111, v221, v109
	ds_bpermute_b32 v110, v221, v108
	s_waitcnt lgkmcnt(0)
	v_pk_add_f32 v[108:109], v[108:109], v[110:111]
	ds_bpermute_b32 v111, v222, v109
	ds_bpermute_b32 v110, v222, v108
	s_waitcnt lgkmcnt(0)
	v_pk_add_f32 v[108:109], v[108:109], v[110:111]
	s_nop 0
	v_pk_mul_f32 v[108:109], v[108:109], s[6:7] op_sel_hi:[1,0]
	s_nop 0
	v_fma_f32 v110, -v109, v109, v108
	v_max_f32_e32 v110, 0, v110
	v_add_f32_e32 v110, 0x358637bd, v110
	v_cmp_gt_f32_e32 vcc, s22, v110
	v_mul_f32_e32 v111, 0x4b800000, v110
	v_pk_add_f32 v[94:95], v[94:95], v[108:109] op_sel:[0,1] neg_lo:[0,1] neg_hi:[0,1]
	v_cndmask_b32_e32 v110, v110, v111, vcc
	v_rsq_f32_e32 v110, v110
	v_pk_add_f32 v[96:97], v[96:97], v[108:109] op_sel:[0,1] neg_lo:[0,1] neg_hi:[0,1]
	v_pk_add_f32 v[90:91], v[90:91], v[108:109] op_sel:[0,1] neg_lo:[0,1] neg_hi:[0,1]
	v_pk_add_f32 v[92:93], v[92:93], v[108:109] op_sel:[0,1] neg_lo:[0,1] neg_hi:[0,1]
	v_mul_f32_e32 v111, 0x45800000, v110
	v_cndmask_b32_e32 v110, v110, v111, vcc
	v_pk_mul_f32 v[94:95], v[94:95], v[110:111] op_sel_hi:[1,0]
	s_nop 0
	v_pk_fma_f32 v[94:95], v[10:11], v[94:95], v[14:15]
	s_nop 0
	v_mul_f32_e32 v111, 0xbfb8aa3b, v94
	v_exp_f32_e32 v111, v111
	s_nop 0
	v_add_f32_e32 v111, 1.0, v111
	v_rcp_f32_e32 v112, v111
	v_mul_f32_e32 v111, 0xbfb8aa3b, v95
	v_exp_f32_e32 v111, v111
	s_nop 0
	v_add_f32_e32 v111, 1.0, v111
	v_rcp_f32_e32 v113, v111
	v_pk_mul_f32 v[96:97], v[96:97], v[110:111] op_sel_hi:[1,0]
	v_pk_mul_f32 v[90:91], v[90:91], v[110:111] op_sel_hi:[1,0]
	v_pk_fma_f32 v[96:97], v[12:13], v[96:97], v[16:17]
	v_pk_mul_f32 v[94:95], v[94:95], v[112:113]
	v_pk_fma_f32 v[90:91], v[2:3], v[90:91], v[6:7]
	v_pk_mul_f32 v[94:95], v[94:95], v[100:101]
	v_pk_mul_f32 v[92:93], v[92:93], v[110:111] op_sel_hi:[1,0]
	v_cvt_pk_bf16_f32 v94, v94, v95
	v_mul_f32_e32 v95, 0xbfb8aa3b, v96
	v_exp_f32_e32 v95, v95
	v_pk_fma_f32 v[92:93], v[4:5], v[92:93], v[8:9]
	v_add_f32_e32 v95, 1.0, v95
	v_rcp_f32_e32 v100, v95
	v_mul_f32_e32 v95, 0xbfb8aa3b, v97
	v_exp_f32_e32 v95, v95
	s_nop 0
	v_add_f32_e32 v95, 1.0, v95
	v_rcp_f32_e32 v101, v95
	s_nop 0
	v_pk_mul_f32 v[96:97], v[96:97], v[100:101]
	s_nop 0
	v_pk_mul_f32 v[96:97], v[96:97], v[102:103]
	s_nop 0
	v_cvt_pk_bf16_f32 v95, v96, v97
	v_mul_f32_e32 v96, 0xbfb8aa3b, v90
	v_mul_f32_e32 v97, 0xbfb8aa3b, v91
	v_exp_f32_e32 v96, v96
	v_exp_f32_e32 v97, v97
	v_add_f32_e32 v96, 1.0, v96
	v_add_f32_e32 v97, 1.0, v97
	v_rcp_f32_e32 v96, v96
	v_rcp_f32_e32 v97, v97
	s_nop 0
	v_pk_mul_f32 v[90:91], v[90:91], v[96:97]
	s_nop 0
	v_pk_mul_f32 v[90:91], v[90:91], v[104:105]
	s_nop 0
	v_cvt_pk_bf16_f32 v90, v90, v91
	v_mul_f32_e32 v91, 0xbfb8aa3b, v92
	v_exp_f32_e32 v91, v91
	s_nop 0
	v_add_f32_e32 v91, 1.0, v91
	v_rcp_f32_e32 v96, v91
	v_mul_f32_e32 v91, 0xbfb8aa3b, v93
	v_exp_f32_e32 v91, v91
	s_nop 0
	v_add_f32_e32 v91, 1.0, v91
	v_rcp_f32_e32 v97, v91
	s_nop 0
	v_pk_mul_f32 v[92:93], v[92:93], v[96:97]
	s_nop 0
	v_pk_mul_f32 v[92:93], v[92:93], v[106:107]
	s_nop 0
	v_cvt_pk_bf16_f32 v91, v92, v93
	v_lshlrev_b64 v[92:93], 11, v[98:99]
	v_add_u32_e32 v98, 0x2002, v120
	v_lshl_add_u64 v[92:93], v[88:89], 0, v[92:93]
	v_ashrrev_i32_e32 v99, 31, v98
	global_store_dwordx2 v[92:93], v[94:95], off
	global_store_dwordx2 v[92:93], v[90:91], off offset:512
	v_lshlrev_b64 v[90:91], 10, v[98:99]
	v_lshl_add_u64 v[90:91], v[86:87], 0, v[90:91]
	ds_read_b128 v[94:97], v224
	s_waitcnt lgkmcnt(0)
	v_mov_b32_e32 v114, v94
	v_mov_b32_e32 v115, v96
	v_pk_mul_f32 v[114:115], v[114:115], v[114:115]
	v_pk_mul_f32 v[116:117], v[94:95], v[94:95]
	v_mov_b32_e32 v118, v114
	v_mov_b32_e32 v119, v94
	v_mov_b32_e32 v116, v117
	v_mov_b32_e32 v117, v95
	v_pk_mul_f32 v[112:113], v[96:97], v[96:97]
	v_pk_add_f32 v[116:117], v[118:119], v[116:117]
	v_pk_mov_b32 v[114:115], v[114:115], v[96:97] op_sel:[1,0]
	v_mov_b32_e32 v112, v113
	v_pk_add_f32 v[114:115], v[116:117], v[114:115]
	v_mov_b32_e32 v113, v97
	v_pk_add_f32 v[112:113], v[114:115], v[112:113]
	v_lshlrev_b32_e32 v100, 16, v136
	v_and_b32_e32 v101, 0xffff0000, v136
	v_lshlrev_b32_e32 v102, 16, v137
	v_and_b32_e32 v103, 0xffff0000, v137
	v_lshlrev_b32_e32 v104, 16, v138
	v_and_b32_e32 v105, 0xffff0000, v138
	v_lshlrev_b32_e32 v106, 16, v139
	v_and_b32_e32 v107, 0xffff0000, v139
	ds_read_b128 v[90:93], v224 offset:1024
	s_waitcnt lgkmcnt(0)
	v_pk_mul_f32 v[110:111], v[90:91], v[90:91]
	s_nop 0
	v_mov_b32_e32 v114, v110
	v_mov_b32_e32 v115, v90
	v_pk_mul_f32 v[108:109], v[92:93], v[92:93]
	v_pk_add_f32 v[112:113], v[112:113], v[114:115]
	v_mov_b32_e32 v110, v111
	v_mov_b32_e32 v111, v91
	v_pk_add_f32 v[110:111], v[112:113], v[110:111]
	v_mov_b32_e32 v112, v108
	v_mov_b32_e32 v113, v92
	v_pk_add_f32 v[110:111], v[110:111], v[112:113]
	v_mov_b32_e32 v108, v109
	v_mov_b32_e32 v109, v93
	v_pk_add_f32 v[108:109], v[110:111], v[108:109]
	ds_bpermute_b32 v111, v217, v109
	ds_bpermute_b32 v110, v217, v108
	s_waitcnt lgkmcnt(0)
	v_pk_add_f32 v[108:109], v[108:109], v[110:111]
	ds_bpermute_b32 v111, v218, v109
	ds_bpermute_b32 v110, v218, v108
	s_waitcnt lgkmcnt(0)
	v_pk_add_f32 v[108:109], v[108:109], v[110:111]
	ds_bpermute_b32 v111, v219, v109
	ds_bpermute_b32 v110, v219, v108
	s_waitcnt lgkmcnt(0)
	v_pk_add_f32 v[108:109], v[108:109], v[110:111]
	ds_bpermute_b32 v111, v220, v109
	ds_bpermute_b32 v110, v220, v108
	s_waitcnt lgkmcnt(0)
	v_pk_add_f32 v[108:109], v[108:109], v[110:111]
	ds_bpermute_b32 v111, v221, v109
	ds_bpermute_b32 v110, v221, v108
	s_waitcnt lgkmcnt(0)
	v_pk_add_f32 v[108:109], v[108:109], v[110:111]
	ds_bpermute_b32 v111, v222, v109
	ds_bpermute_b32 v110, v222, v108
	s_waitcnt lgkmcnt(0)
	v_pk_add_f32 v[108:109], v[108:109], v[110:111]
	s_nop 0
	v_pk_mul_f32 v[108:109], v[108:109], s[6:7] op_sel_hi:[1,0]
	s_nop 0
	v_fma_f32 v110, -v109, v109, v108
	v_max_f32_e32 v110, 0, v110
	v_add_f32_e32 v110, 0x358637bd, v110
	v_cmp_gt_f32_e32 vcc, s22, v110
	v_mul_f32_e32 v111, 0x4b800000, v110
	v_pk_add_f32 v[94:95], v[94:95], v[108:109] op_sel:[0,1] neg_lo:[0,1] neg_hi:[0,1]
	v_cndmask_b32_e32 v110, v110, v111, vcc
	v_rsq_f32_e32 v110, v110
	v_pk_add_f32 v[96:97], v[96:97], v[108:109] op_sel:[0,1] neg_lo:[0,1] neg_hi:[0,1]
	v_pk_add_f32 v[90:91], v[90:91], v[108:109] op_sel:[0,1] neg_lo:[0,1] neg_hi:[0,1]
	v_pk_add_f32 v[92:93], v[92:93], v[108:109] op_sel:[0,1] neg_lo:[0,1] neg_hi:[0,1]
	v_mul_f32_e32 v111, 0x45800000, v110
	v_cndmask_b32_e32 v110, v110, v111, vcc
	v_pk_mul_f32 v[94:95], v[94:95], v[110:111] op_sel_hi:[1,0]
	s_nop 0
	v_pk_fma_f32 v[94:95], v[10:11], v[94:95], v[14:15]
	s_nop 0
	v_mul_f32_e32 v111, 0xbfb8aa3b, v94
	v_exp_f32_e32 v111, v111
	s_nop 0
	v_add_f32_e32 v111, 1.0, v111
	v_rcp_f32_e32 v112, v111
	v_mul_f32_e32 v111, 0xbfb8aa3b, v95
	v_exp_f32_e32 v111, v111
	s_nop 0
	v_add_f32_e32 v111, 1.0, v111
	v_rcp_f32_e32 v113, v111
	v_pk_mul_f32 v[96:97], v[96:97], v[110:111] op_sel_hi:[1,0]
	v_pk_mul_f32 v[90:91], v[90:91], v[110:111] op_sel_hi:[1,0]
	v_pk_fma_f32 v[96:97], v[12:13], v[96:97], v[16:17]
	v_pk_mul_f32 v[94:95], v[94:95], v[112:113]
	v_pk_fma_f32 v[90:91], v[2:3], v[90:91], v[6:7]
	v_pk_mul_f32 v[94:95], v[94:95], v[100:101]
	v_pk_mul_f32 v[92:93], v[92:93], v[110:111] op_sel_hi:[1,0]
	v_cvt_pk_bf16_f32 v94, v94, v95
	v_mul_f32_e32 v95, 0xbfb8aa3b, v96
	v_exp_f32_e32 v95, v95
	v_pk_fma_f32 v[92:93], v[4:5], v[92:93], v[8:9]
	v_add_f32_e32 v95, 1.0, v95
	v_rcp_f32_e32 v100, v95
	v_mul_f32_e32 v95, 0xbfb8aa3b, v97
	v_exp_f32_e32 v95, v95
	s_nop 0
	v_add_f32_e32 v95, 1.0, v95
	v_rcp_f32_e32 v101, v95
	s_nop 0
	v_pk_mul_f32 v[96:97], v[96:97], v[100:101]
	s_nop 0
	v_pk_mul_f32 v[96:97], v[96:97], v[102:103]
	s_nop 0
	v_cvt_pk_bf16_f32 v95, v96, v97
	v_mul_f32_e32 v96, 0xbfb8aa3b, v90
	v_mul_f32_e32 v97, 0xbfb8aa3b, v91
	v_exp_f32_e32 v96, v96
	v_exp_f32_e32 v97, v97
	v_add_f32_e32 v96, 1.0, v96
	v_add_f32_e32 v97, 1.0, v97
	v_rcp_f32_e32 v96, v96
	v_rcp_f32_e32 v97, v97
	s_nop 0
	v_pk_mul_f32 v[90:91], v[90:91], v[96:97]
	s_nop 0
	v_pk_mul_f32 v[90:91], v[90:91], v[104:105]
	s_nop 0
	v_cvt_pk_bf16_f32 v90, v90, v91
	v_mul_f32_e32 v91, 0xbfb8aa3b, v92
	v_exp_f32_e32 v91, v91
	s_nop 0
	v_add_f32_e32 v91, 1.0, v91
	v_rcp_f32_e32 v96, v91
	v_mul_f32_e32 v91, 0xbfb8aa3b, v93
	v_exp_f32_e32 v91, v91
	s_nop 0
	v_add_f32_e32 v91, 1.0, v91
	v_rcp_f32_e32 v97, v91
	s_nop 0
	v_pk_mul_f32 v[92:93], v[92:93], v[96:97]
	s_nop 0
	v_pk_mul_f32 v[92:93], v[92:93], v[106:107]
	s_nop 0
	v_cvt_pk_bf16_f32 v91, v92, v93
	v_lshlrev_b64 v[92:93], 11, v[98:99]
	v_add_u32_e32 v98, 0x2003, v120
	v_lshl_add_u64 v[92:93], v[88:89], 0, v[92:93]
	v_ashrrev_i32_e32 v99, 31, v98
	global_store_dwordx2 v[92:93], v[94:95], off
	global_store_dwordx2 v[92:93], v[90:91], off offset:512
	v_lshlrev_b64 v[90:91], 10, v[98:99]
	v_lshl_add_u64 v[90:91], v[86:87], 0, v[90:91]
	ds_read_b128 v[94:97], v225
	s_waitcnt lgkmcnt(0)
	v_mov_b32_e32 v114, v94
	v_mov_b32_e32 v115, v96
	v_pk_mul_f32 v[114:115], v[114:115], v[114:115]
	v_pk_mul_f32 v[116:117], v[94:95], v[94:95]
	v_mov_b32_e32 v118, v114
	v_mov_b32_e32 v119, v94
	v_mov_b32_e32 v116, v117
	v_mov_b32_e32 v117, v95
	v_pk_mul_f32 v[112:113], v[96:97], v[96:97]
	v_pk_add_f32 v[116:117], v[118:119], v[116:117]
	v_pk_mov_b32 v[114:115], v[114:115], v[96:97] op_sel:[1,0]
	v_mov_b32_e32 v112, v113
	v_pk_add_f32 v[114:115], v[116:117], v[114:115]
	v_mov_b32_e32 v113, v97
	v_pk_add_f32 v[112:113], v[114:115], v[112:113]
	v_lshlrev_b32_e32 v100, 16, v140
	v_and_b32_e32 v101, 0xffff0000, v140
	v_lshlrev_b32_e32 v102, 16, v141
	v_and_b32_e32 v103, 0xffff0000, v141
	v_lshlrev_b32_e32 v104, 16, v142
	v_and_b32_e32 v105, 0xffff0000, v142
	v_lshlrev_b32_e32 v106, 16, v143
	v_and_b32_e32 v107, 0xffff0000, v143
	ds_read_b128 v[90:93], v225 offset:1024
	s_waitcnt lgkmcnt(0)
	v_pk_mul_f32 v[110:111], v[90:91], v[90:91]
	s_nop 0
	v_mov_b32_e32 v114, v110
	v_mov_b32_e32 v115, v90
	v_pk_mul_f32 v[108:109], v[92:93], v[92:93]
	v_pk_add_f32 v[112:113], v[112:113], v[114:115]
	v_mov_b32_e32 v110, v111
	v_mov_b32_e32 v111, v91
	v_pk_add_f32 v[110:111], v[112:113], v[110:111]
	v_mov_b32_e32 v112, v108
	v_mov_b32_e32 v113, v92
	v_pk_add_f32 v[110:111], v[110:111], v[112:113]
	v_mov_b32_e32 v108, v109
	v_mov_b32_e32 v109, v93
	v_pk_add_f32 v[108:109], v[110:111], v[108:109]
	ds_bpermute_b32 v111, v217, v109
	ds_bpermute_b32 v110, v217, v108
	s_waitcnt lgkmcnt(0)
	v_pk_add_f32 v[108:109], v[108:109], v[110:111]
	ds_bpermute_b32 v111, v218, v109
	ds_bpermute_b32 v110, v218, v108
	s_waitcnt lgkmcnt(0)
	v_pk_add_f32 v[108:109], v[108:109], v[110:111]
	ds_bpermute_b32 v111, v219, v109
	ds_bpermute_b32 v110, v219, v108
	s_waitcnt lgkmcnt(0)
	v_pk_add_f32 v[108:109], v[108:109], v[110:111]
	ds_bpermute_b32 v111, v220, v109
	ds_bpermute_b32 v110, v220, v108
	s_waitcnt lgkmcnt(0)
	v_pk_add_f32 v[108:109], v[108:109], v[110:111]
	ds_bpermute_b32 v111, v221, v109
	ds_bpermute_b32 v110, v221, v108
	s_waitcnt lgkmcnt(0)
	v_pk_add_f32 v[108:109], v[108:109], v[110:111]
	ds_bpermute_b32 v111, v222, v109
	ds_bpermute_b32 v110, v222, v108
	s_waitcnt lgkmcnt(0)
	v_pk_add_f32 v[108:109], v[108:109], v[110:111]
	s_nop 0
	v_pk_mul_f32 v[108:109], v[108:109], s[6:7] op_sel_hi:[1,0]
	s_nop 0
	v_fma_f32 v110, -v109, v109, v108
	v_max_f32_e32 v110, 0, v110
	v_add_f32_e32 v110, 0x358637bd, v110
	v_cmp_gt_f32_e32 vcc, s22, v110
	v_mul_f32_e32 v111, 0x4b800000, v110
	v_pk_add_f32 v[94:95], v[94:95], v[108:109] op_sel:[0,1] neg_lo:[0,1] neg_hi:[0,1]
	v_cndmask_b32_e32 v110, v110, v111, vcc
	v_rsq_f32_e32 v110, v110
	s_nop 0
	v_mul_f32_e32 v111, 0x45800000, v110
	v_cndmask_b32_e32 v110, v110, v111, vcc
	v_pk_mul_f32 v[94:95], v[94:95], v[110:111] op_sel_hi:[1,0]
	v_cmp_lt_i32_e32 vcc, s23, v1
	v_pk_fma_f32 v[10:11], v[10:11], v[94:95], v[14:15]
	s_or_b64 s[4:5], vcc, s[4:5]
	v_mul_f32_e32 v14, 0xbfb8aa3b, v10
	v_mul_f32_e32 v15, 0xbfb8aa3b, v11
	v_exp_f32_e32 v14, v14
	v_exp_f32_e32 v15, v15
	v_add_f32_e32 v14, 1.0, v14
	v_add_f32_e32 v15, 1.0, v15
	v_rcp_f32_e32 v14, v14
	v_rcp_f32_e32 v15, v15
	s_nop 0
	v_pk_mul_f32 v[10:11], v[10:11], v[14:15]
	v_pk_add_f32 v[14:15], v[96:97], v[108:109] op_sel:[0,1] neg_lo:[0,1] neg_hi:[0,1]
	v_pk_mul_f32 v[10:11], v[10:11], v[100:101]
	v_pk_mul_f32 v[14:15], v[14:15], v[110:111] op_sel_hi:[1,0]
	v_cvt_pk_bf16_f32 v10, v10, v11
	v_pk_fma_f32 v[12:13], v[12:13], v[14:15], v[16:17]
	s_nop 0
	v_mul_f32_e32 v11, 0xbfb8aa3b, v12
	v_exp_f32_e32 v11, v11
	s_nop 0
	v_add_f32_e32 v11, 1.0, v11
	v_rcp_f32_e32 v14, v11
	v_mul_f32_e32 v11, 0xbfb8aa3b, v13
	v_exp_f32_e32 v11, v11
	s_nop 0
	v_add_f32_e32 v11, 1.0, v11
	v_rcp_f32_e32 v15, v11
	s_nop 0
	v_pk_mul_f32 v[12:13], v[12:13], v[14:15]
	s_nop 0
	v_pk_mul_f32 v[12:13], v[12:13], v[102:103]
	s_nop 0
	v_cvt_pk_bf16_f32 v11, v12, v13
	v_pk_add_f32 v[12:13], v[90:91], v[108:109] op_sel:[0,1] neg_lo:[0,1] neg_hi:[0,1]
	s_nop 0
	v_pk_mul_f32 v[12:13], v[12:13], v[110:111] op_sel_hi:[1,0]
	s_nop 0
	v_pk_fma_f32 v[2:3], v[2:3], v[12:13], v[6:7]
	s_nop 0
	v_mul_f32_e32 v6, 0xbfb8aa3b, v2
	v_mul_f32_e32 v7, 0xbfb8aa3b, v3
	v_exp_f32_e32 v6, v6
	v_exp_f32_e32 v7, v7
	v_add_f32_e32 v6, 1.0, v6
	v_add_f32_e32 v7, 1.0, v7
	v_rcp_f32_e32 v6, v6
	v_rcp_f32_e32 v7, v7
	s_nop 0
	v_pk_mul_f32 v[2:3], v[2:3], v[6:7]
	v_pk_add_f32 v[6:7], v[92:93], v[108:109] op_sel:[0,1] neg_lo:[0,1] neg_hi:[0,1]
	v_pk_mul_f32 v[2:3], v[2:3], v[104:105]
	v_pk_mul_f32 v[6:7], v[6:7], v[110:111] op_sel_hi:[1,0]
	v_cvt_pk_bf16_f32 v2, v2, v3
	v_pk_fma_f32 v[4:5], v[4:5], v[6:7], v[8:9]
	s_nop 0
	v_mul_f32_e32 v3, 0xbfb8aa3b, v4
	v_exp_f32_e32 v3, v3
	s_nop 0
	v_add_f32_e32 v3, 1.0, v3
	v_rcp_f32_e32 v6, v3
	v_mul_f32_e32 v3, 0xbfb8aa3b, v5
	v_exp_f32_e32 v3, v3
	s_nop 0
	v_add_f32_e32 v3, 1.0, v3
	v_rcp_f32_e32 v7, v3
	s_nop 0
	v_pk_mul_f32 v[4:5], v[4:5], v[6:7]
	s_nop 0
	v_pk_mul_f32 v[4:5], v[4:5], v[106:107]
	s_nop 0
	v_cvt_pk_bf16_f32 v3, v4, v5
	v_lshlrev_b64 v[4:5], 11, v[98:99]
	v_lshl_add_u64 v[4:5], v[88:89], 0, v[4:5]
	global_store_dwordx2 v[4:5], v[10:11], off
	global_store_dwordx2 v[4:5], v[2:3], off offset:512
	s_andn2_b64 exec, exec, s[4:5]
	s_cbranch_execnz .LBB0_555
